# speedup vs baseline: 1.0074x; 1.0018x over previous
; #define NT_LOAD(p) __builtin_nontemporal_load(p)
; __device__ __forceinline__ float lru_step(float la, float bx, float h) { float a = __expf(la); return a * h + __builtin_amdgcn_sqrtf(fmaxf(1.f - a * a, 0.f)) * bx; }
; __device__ __forceinline__ void phase4c(KP pp, int l) {
;     ...
;     { const unsigned char* LA = LA8B + base; const h16* Bv = LAB + (size_t)CT * D + base;
;       float2 cr = *(const float2*)(CARRY + (size_t)seg * D + c2); float h0 = cr.x, h1 = cr.y;
; #pragma unroll 1
;       for (int tb = 0; tb < 64; tb += 16) {
;         unsigned short la[16]; h16x2 bb[16];
; #pragma unroll
;         for (int i = 0; i < 16; ++i) { la[i] = NT_LOAD((const unsigned short*)(LA + (size_t)(tb + i) * D)); bb[i] = NT_LOAD((const h16x2*)(Bv + (size_t)(tb + i) * D)); }
; #pragma unroll
;         for (int i = 0; i < 16; ++i) {
;           h0 = lru_step(kf0 * (float)(la[i] & 255), (float)bb[i][0], h0); h1 = lru_step(kf1 * (float)(la[i] >> 8), (float)bb[i][1], h1);
;           h16x2 o; o[0] = (h16)h0; o[1] = (h16)h1; hf[(tb + i) * 512 + tid_] = o; } } }
.LBB0_59:
	s_mov_b32 s100, 0x3fb8aa3b
	s_mov_b32 s101, 0xffff0000
	v_lshl_add_u64 v[18:19], s[4:5], 0, v[10:11]
	v_add_co_u32_e32 v20, vcc, 0x9a00000, v18
	v_lshl_add_u64 v[28:29], s[4:5], 0, v[12:13]
	s_nop 0
	v_addc_co_u32_e32 v21, vcc, 0, v19, vcc
	global_load_ushort v17, v[20:21], off nt
	v_add_co_u32_e32 v30, vcc, 0xba00000, v28
	s_add_i32 s16, s16, 16
	s_nop 0
	v_addc_co_u32_e32 v31, vcc, 0, v29, vcc
	global_load_dword v27, v[30:31], off nt
	global_load_ushort v32, v[20:21], off offset:1024 nt
	global_load_dword v33, v[30:31], off offset:2048 nt
	global_load_ushort v34, v[20:21], off offset:2048 nt
	v_add_co_u32_e32 v30, vcc, 0xba01000, v28
	s_mov_b64 s[18:19], 0x4000
	s_nop 0
	v_addc_co_u32_e32 v31, vcc, 0, v29, vcc
	global_load_dword v35, v[30:31], off nt
	global_load_ushort v36, v[20:21], off offset:3072 nt
	global_load_dword v37, v[30:31], off offset:2048 nt
	v_add_co_u32_e32 v20, vcc, 0x9a01000, v18
	v_lshl_add_u64 v[12:13], v[12:13], 0, s[50:51]
	s_nop 0
	v_addc_co_u32_e32 v21, vcc, 0, v19, vcc
	v_add_co_u32_e32 v30, vcc, 0xba02000, v28
	global_load_ushort v38, v[20:21], off nt
	s_nop 0
	v_addc_co_u32_e32 v31, vcc, 0, v29, vcc
	global_load_dword v39, v[30:31], off nt
	global_load_ushort v40, v[20:21], off offset:1024 nt
	global_load_dword v41, v[30:31], off offset:2048 nt
	global_load_ushort v42, v[20:21], off offset:2048 nt
	v_add_co_u32_e32 v30, vcc, 0xba03000, v28
	v_lshl_add_u64 v[10:11], v[10:11], 0, s[18:19]
	s_nop 0
	v_addc_co_u32_e32 v31, vcc, 0, v29, vcc
	global_load_dword v43, v[30:31], off nt
	global_load_ushort v44, v[20:21], off offset:3072 nt
	global_load_dword v45, v[30:31], off offset:2048 nt
	v_add_co_u32_e32 v20, vcc, 0x9a02000, v18
	s_cmp_lt_u32 s16, 48
	s_nop 0
	v_addc_co_u32_e32 v21, vcc, 0, v19, vcc
	v_add_co_u32_e32 v30, vcc, 0xba04000, v28
	global_load_ushort v46, v[20:21], off nt
	s_nop 0
	v_addc_co_u32_e32 v31, vcc, 0, v29, vcc
	global_load_dword v47, v[30:31], off nt
	global_load_ushort v48, v[20:21], off offset:1024 nt
	global_load_dword v49, v[30:31], off offset:2048 nt
	global_load_ushort v50, v[20:21], off offset:2048 nt
	v_add_co_u32_e32 v30, vcc, 0xba05000, v28
	s_nop 1
	v_addc_co_u32_e32 v31, vcc, 0, v29, vcc
	v_add_co_u32_e32 v18, vcc, 0x9a03000, v18
	global_load_dword v51, v[30:31], off nt
	global_load_ushort v52, v[20:21], off offset:3072 nt
	global_load_dword v53, v[30:31], off offset:2048 nt
	v_addc_co_u32_e32 v19, vcc, 0, v19, vcc
	v_add_co_u32_e32 v20, vcc, 0xba06000, v28
	global_load_ushort v54, v[18:19], off nt
	s_nop 0
	v_addc_co_u32_e32 v21, vcc, 0, v29, vcc
	global_load_dword v55, v[20:21], off nt
	global_load_ushort v56, v[18:19], off offset:1024 nt
	global_load_dword v57, v[20:21], off offset:2048 nt
	global_load_ushort v58, v[18:19], off offset:2048 nt
	v_add_co_u32_e32 v20, vcc, 0xba07000, v28
	s_waitcnt vmcnt(27)
	v_cvt_f32_f16_e32 v28, v27
	v_addc_co_u32_e32 v21, vcc, 0, v29, vcc
	global_load_dword v59, v[20:21], off nt
	global_load_ushort v60, v[18:19], off offset:3072 nt
	global_load_dword v61, v[20:21], off offset:2048 nt
	v_cvt_f32_ubyte0_e32 v18, v17
	v_mul_f32_e32 v18, v22, v18
	v_mul_f32_e32 v18, s100, v18
	v_exp_f32_e32 v18, v18
	v_cvt_f32_ubyte1_e32 v17, v17
	v_mul_f32_e32 v17, v23, v17
	v_mul_f32_e32 v17, s100, v17
	v_fma_f32 v19, -v18, v18, 1.0
	v_max_f32_e32 v19, 0, v19
	v_sqrt_f32_e32 v20, v19
	v_exp_f32_e32 v19, v17
	v_cvt_f32_f16_sdwa v29, v27 dst_sel:DWORD dst_unused:UNUSED_PAD src0_sel:WORD_1
	v_fma_f32 v17, -v19, v19, 1.0
	v_max_f32_e32 v17, 0, v17
	v_sqrt_f32_e32 v21, v17
	s_nop 0
	v_pk_mul_f32 v[20:21], v[20:21], v[28:29]
	s_nop 0
	v_pk_fma_f32 v[14:15], v[14:15], v[18:19], v[20:21]
	s_waitcnt vmcnt(29)
	v_cvt_f32_ubyte0_e32 v18, v32
	v_mul_f32_e32 v18, v22, v18
	v_mul_f32_e32 v18, s100, v18
	v_exp_f32_e32 v18, v18
	s_waitcnt vmcnt(28)
	v_cvt_f32_f16_e32 v28, v33
	v_cvt_f32_f16_sdwa v29, v33 dst_sel:DWORD dst_unused:UNUSED_PAD src0_sel:WORD_1
	v_cvt_pk_f16_f32 v17, v14, v15
	v_fma_f32 v19, -v18, v18, 1.0
	v_max_f32_e32 v19, 0, v19
	v_sqrt_f32_e32 v20, v19
	v_cvt_f32_ubyte1_e32 v19, v32
	v_mul_f32_e32 v19, v23, v19
	v_mul_f32_e32 v19, s100, v19
	v_exp_f32_e32 v19, v19
	s_nop 0
	v_fma_f32 v21, -v19, v19, 1.0
	v_max_f32_e32 v21, 0, v21
	v_sqrt_f32_e32 v21, v21
	s_nop 0
	v_pk_mul_f32 v[20:21], v[20:21], v[28:29]
	s_nop 0
	v_pk_fma_f32 v[14:15], v[18:19], v[14:15], v[20:21]
	s_waitcnt vmcnt(26)
	v_cvt_f32_f16_e32 v28, v35
	v_cvt_pk_f16_f32 v18, v14, v15
	ds_write2st64_b32 v16, v17, v18 offset1:8
	v_cvt_f32_ubyte0_e32 v17, v34
	v_mul_f32_e32 v17, v22, v17
	v_mul_f32_e32 v17, s100, v17
	v_exp_f32_e32 v18, v17
	v_cvt_f32_f16_sdwa v29, v35 dst_sel:DWORD dst_unused:UNUSED_PAD src0_sel:WORD_1
	v_fma_f32 v17, -v18, v18, 1.0
	v_max_f32_e32 v17, 0, v17
	v_sqrt_f32_e32 v20, v17
	v_cvt_f32_ubyte1_e32 v17, v34
	v_mul_f32_e32 v17, v23, v17
	v_mul_f32_e32 v17, s100, v17
	v_exp_f32_e32 v19, v17
	s_nop 0
	v_fma_f32 v17, -v19, v19, 1.0
	v_max_f32_e32 v17, 0, v17
	v_sqrt_f32_e32 v21, v17
	s_nop 0
	v_pk_mul_f32 v[20:21], v[20:21], v[28:29]
	s_nop 0
	v_pk_fma_f32 v[14:15], v[18:19], v[14:15], v[20:21]
	s_waitcnt vmcnt(25)
	v_cvt_f32_ubyte0_e32 v18, v36
	v_mul_f32_e32 v18, v22, v18
	v_mul_f32_e32 v18, s100, v18
	v_exp_f32_e32 v18, v18
	s_waitcnt vmcnt(24)
	v_cvt_f32_f16_e32 v28, v37
	v_cvt_f32_f16_sdwa v29, v37 dst_sel:DWORD dst_unused:UNUSED_PAD src0_sel:WORD_1
	v_cvt_pk_f16_f32 v17, v14, v15
	v_fma_f32 v19, -v18, v18, 1.0
	v_max_f32_e32 v19, 0, v19
	v_sqrt_f32_e32 v20, v19
	v_cvt_f32_ubyte1_e32 v19, v36
	v_mul_f32_e32 v19, v23, v19
	v_mul_f32_e32 v19, s100, v19
	v_exp_f32_e32 v19, v19
	s_nop 0
	v_fma_f32 v21, -v19, v19, 1.0
	v_max_f32_e32 v21, 0, v21
	v_sqrt_f32_e32 v21, v21
	s_nop 0
	v_pk_mul_f32 v[20:21], v[20:21], v[28:29]
	s_nop 0
	v_pk_fma_f32 v[14:15], v[18:19], v[14:15], v[20:21]
	s_waitcnt vmcnt(22)
; #define NT_LOAD(p) __builtin_nontemporal_load(p)
; __device__ __forceinline__ float lru_step(float la, float bx, float h) { float a = __expf(la); return a * h + __builtin_amdgcn_sqrtf(fmaxf(1.f - a * a, 0.f)) * bx; }
; __device__ __forceinline__ void phase4c(KP pp, int l) {
;     ...
;         for (int i = 0; i < 16; ++i) { la[i] = NT_LOAD((const unsigned short*)(LA + (size_t)(tb + i) * D)); bb[i] = NT_LOAD((const h16x2*)(Bv + (size_t)(tb + i) * D)); }
; #pragma unroll
;         for (int i = 0; i < 16; ++i) {
;           h0 = lru_step(kf0 * (float)(la[i] & 255), (float)bb[i][0], h0); h1 = lru_step(kf1 * (float)(la[i] >> 8), (float)bb[i][1], h1);
;           h16x2 o; o[0] = (h16)h0; o[1] = (h16)h1; hf[(tb + i) * 512 + tid_] = o; } } }
	v_cvt_f32_f16_e32 v28, v39
	v_cvt_pk_f16_f32 v18, v14, v15
	ds_write2st64_b32 v16, v17, v18 offset0:16 offset1:24
	v_cvt_f32_ubyte0_e32 v17, v38
	v_mul_f32_e32 v17, v22, v17
	v_mul_f32_e32 v17, s100, v17
	v_exp_f32_e32 v18, v17
	v_cvt_f32_f16_sdwa v29, v39 dst_sel:DWORD dst_unused:UNUSED_PAD src0_sel:WORD_1
	v_fma_f32 v17, -v18, v18, 1.0
	v_max_f32_e32 v17, 0, v17
	v_sqrt_f32_e32 v20, v17
	v_cvt_f32_ubyte1_e32 v17, v38
	v_mul_f32_e32 v17, v23, v17
	v_mul_f32_e32 v17, s100, v17
	v_exp_f32_e32 v19, v17
	s_nop 0
	v_fma_f32 v17, -v19, v19, 1.0
	v_max_f32_e32 v17, 0, v17
	v_sqrt_f32_e32 v21, v17
	s_nop 0
	v_pk_mul_f32 v[20:21], v[20:21], v[28:29]
	s_nop 0
	v_pk_fma_f32 v[14:15], v[18:19], v[14:15], v[20:21]
	s_waitcnt vmcnt(21)
	v_cvt_f32_ubyte0_e32 v18, v40
	v_mul_f32_e32 v18, v22, v18
	v_mul_f32_e32 v18, s100, v18
	v_exp_f32_e32 v18, v18
	s_waitcnt vmcnt(20)
	v_cvt_f32_f16_e32 v28, v41
	v_cvt_f32_f16_sdwa v29, v41 dst_sel:DWORD dst_unused:UNUSED_PAD src0_sel:WORD_1
	v_cvt_pk_f16_f32 v17, v14, v15
	v_fma_f32 v19, -v18, v18, 1.0
	v_max_f32_e32 v19, 0, v19
	v_sqrt_f32_e32 v20, v19
	v_cvt_f32_ubyte1_e32 v19, v40
	v_mul_f32_e32 v19, v23, v19
	v_mul_f32_e32 v19, s100, v19
	v_exp_f32_e32 v19, v19
	s_nop 0
	v_fma_f32 v21, -v19, v19, 1.0
	v_max_f32_e32 v21, 0, v21
	v_sqrt_f32_e32 v21, v21
	s_nop 0
	v_pk_mul_f32 v[20:21], v[20:21], v[28:29]
	s_nop 0
	v_pk_fma_f32 v[14:15], v[18:19], v[14:15], v[20:21]
	s_waitcnt vmcnt(18)
	v_cvt_f32_f16_e32 v28, v43
	v_cvt_pk_f16_f32 v18, v14, v15
	ds_write2st64_b32 v16, v17, v18 offset0:32 offset1:40
	v_cvt_f32_ubyte0_e32 v17, v42
	v_mul_f32_e32 v17, v22, v17
	v_mul_f32_e32 v17, s100, v17
	v_exp_f32_e32 v18, v17
	v_cvt_f32_f16_sdwa v29, v43 dst_sel:DWORD dst_unused:UNUSED_PAD src0_sel:WORD_1
	v_fma_f32 v17, -v18, v18, 1.0
	v_max_f32_e32 v17, 0, v17
	v_sqrt_f32_e32 v20, v17
	v_cvt_f32_ubyte1_e32 v17, v42
	v_mul_f32_e32 v17, v23, v17
	v_mul_f32_e32 v17, s100, v17
	v_exp_f32_e32 v19, v17
	s_nop 0
	v_fma_f32 v17, -v19, v19, 1.0
	v_max_f32_e32 v17, 0, v17
	v_sqrt_f32_e32 v21, v17
	s_nop 0
	v_pk_mul_f32 v[20:21], v[20:21], v[28:29]
	s_nop 0
	v_pk_fma_f32 v[14:15], v[18:19], v[14:15], v[20:21]
	s_waitcnt vmcnt(17)
	v_cvt_f32_ubyte0_e32 v18, v44
	v_mul_f32_e32 v18, v22, v18
	v_mul_f32_e32 v18, s100, v18
	v_exp_f32_e32 v18, v18
	s_waitcnt vmcnt(16)
	v_cvt_f32_f16_e32 v28, v45
	v_cvt_f32_f16_sdwa v29, v45 dst_sel:DWORD dst_unused:UNUSED_PAD src0_sel:WORD_1
	v_cvt_pk_f16_f32 v17, v14, v15
	v_fma_f32 v19, -v18, v18, 1.0
	v_max_f32_e32 v19, 0, v19
	v_sqrt_f32_e32 v20, v19
	v_cvt_f32_ubyte1_e32 v19, v44
	v_mul_f32_e32 v19, v23, v19
	v_mul_f32_e32 v19, s100, v19
	v_exp_f32_e32 v19, v19
	s_nop 0
	v_fma_f32 v21, -v19, v19, 1.0
	v_max_f32_e32 v21, 0, v21
	v_sqrt_f32_e32 v21, v21
	s_nop 0
	v_pk_mul_f32 v[20:21], v[20:21], v[28:29]
	s_nop 0
	v_pk_fma_f32 v[14:15], v[18:19], v[14:15], v[20:21]
	s_waitcnt vmcnt(14)
	v_cvt_f32_f16_e32 v28, v47
	v_cvt_pk_f16_f32 v18, v14, v15
	ds_write2st64_b32 v16, v17, v18 offset0:48 offset1:56
	v_cvt_f32_ubyte0_e32 v17, v46
	v_mul_f32_e32 v17, v22, v17
	v_mul_f32_e32 v17, s100, v17
	v_exp_f32_e32 v18, v17
	v_cvt_f32_f16_sdwa v29, v47 dst_sel:DWORD dst_unused:UNUSED_PAD src0_sel:WORD_1
	v_fma_f32 v17, -v18, v18, 1.0
	v_max_f32_e32 v17, 0, v17
	v_sqrt_f32_e32 v20, v17
	v_cvt_f32_ubyte1_e32 v17, v46
	v_mul_f32_e32 v17, v23, v17
	v_mul_f32_e32 v17, s100, v17
	v_exp_f32_e32 v19, v17
	s_nop 0
	v_fma_f32 v17, -v19, v19, 1.0
	v_max_f32_e32 v17, 0, v17
	v_sqrt_f32_e32 v21, v17
	s_nop 0
	v_pk_mul_f32 v[20:21], v[20:21], v[28:29]
	s_nop 0
	v_pk_fma_f32 v[14:15], v[18:19], v[14:15], v[20:21]
	s_waitcnt vmcnt(13)
	v_cvt_f32_ubyte0_e32 v18, v48
	v_mul_f32_e32 v18, v22, v18
	v_mul_f32_e32 v18, s100, v18
	v_exp_f32_e32 v18, v18
	s_waitcnt vmcnt(12)
	v_cvt_f32_f16_e32 v28, v49
	v_cvt_f32_f16_sdwa v29, v49 dst_sel:DWORD dst_unused:UNUSED_PAD src0_sel:WORD_1
	v_cvt_pk_f16_f32 v17, v14, v15
	v_fma_f32 v19, -v18, v18, 1.0
	v_max_f32_e32 v19, 0, v19
	v_sqrt_f32_e32 v20, v19
	v_cvt_f32_ubyte1_e32 v19, v48
	v_mul_f32_e32 v19, v23, v19
	v_mul_f32_e32 v19, s100, v19
	v_exp_f32_e32 v19, v19
	s_nop 0
	v_fma_f32 v21, -v19, v19, 1.0
	v_max_f32_e32 v21, 0, v21
	v_sqrt_f32_e32 v21, v21
	s_nop 0
	v_pk_mul_f32 v[20:21], v[20:21], v[28:29]
	s_nop 0
	v_pk_fma_f32 v[14:15], v[18:19], v[14:15], v[20:21]
	s_waitcnt vmcnt(10)
	v_cvt_f32_f16_e32 v28, v51
	v_cvt_pk_f16_f32 v18, v14, v15
	ds_write2st64_b32 v16, v17, v18 offset0:64 offset1:72
	v_cvt_f32_ubyte0_e32 v17, v50
	v_mul_f32_e32 v17, v22, v17
	v_mul_f32_e32 v17, s100, v17
	v_exp_f32_e32 v18, v17
	v_cvt_f32_f16_sdwa v29, v51 dst_sel:DWORD dst_unused:UNUSED_PAD src0_sel:WORD_1
	v_fma_f32 v17, -v18, v18, 1.0
	v_max_f32_e32 v17, 0, v17
	v_sqrt_f32_e32 v20, v17
	v_cvt_f32_ubyte1_e32 v17, v50
	v_mul_f32_e32 v17, v23, v17
	v_mul_f32_e32 v17, s100, v17
	v_exp_f32_e32 v19, v17
	s_nop 0
	v_fma_f32 v17, -v19, v19, 1.0
	v_max_f32_e32 v17, 0, v17
	v_sqrt_f32_e32 v21, v17
	s_waitcnt vmcnt(9)
	v_cvt_f32_ubyte0_e32 v17, v52
	v_mul_f32_e32 v17, v22, v17
	v_mul_f32_e32 v17, s100, v17
	v_pk_mul_f32 v[20:21], v[20:21], v[28:29]
	v_exp_f32_e32 v28, v17
	v_pk_fma_f32 v[14:15], v[18:19], v[14:15], v[20:21]
	s_waitcnt vmcnt(8)
	v_cvt_f32_f16_e32 v18, v53
	v_cvt_f32_f16_sdwa v19, v53 dst_sel:DWORD dst_unused:UNUSED_PAD src0_sel:WORD_1
	v_fma_f32 v17, -v28, v28, 1.0
	v_max_f32_e32 v17, 0, v17
	v_sqrt_f32_e32 v30, v17
	v_cvt_f32_ubyte1_e32 v17, v52
	v_mul_f32_e32 v17, v23, v17
	v_mul_f32_e32 v17, s100, v17
	v_exp_f32_e32 v29, v17
	s_nop 0
	v_fma_f32 v17, -v29, v29, 1.0
	v_max_f32_e32 v17, 0, v17
	v_sqrt_f32_e32 v31, v17
	s_waitcnt vmcnt(7)
; #define NT_LOAD(p) __builtin_nontemporal_load(p)
; __device__ __forceinline__ float lru_step(float la, float bx, float h) { float a = __expf(la); return a * h + __builtin_amdgcn_sqrtf(fmaxf(1.f - a * a, 0.f)) * bx; }
; __device__ __forceinline__ void phase4c(KP pp, int l) {
;     ...
;         for (int i = 0; i < 16; ++i) { la[i] = NT_LOAD((const unsigned short*)(LA + (size_t)(tb + i) * D)); bb[i] = NT_LOAD((const h16x2*)(Bv + (size_t)(tb + i) * D)); }
; #pragma unroll
;         for (int i = 0; i < 16; ++i) {
;           h0 = lru_step(kf0 * (float)(la[i] & 255), (float)bb[i][0], h0); h1 = lru_step(kf1 * (float)(la[i] >> 8), (float)bb[i][1], h1);
;           h16x2 o; o[0] = (h16)h0; o[1] = (h16)h1; hf[(tb + i) * 512 + tid_] = o; } } }
;     { const unsigned char* LA = LA8B + (size_t)2 * CT * D * 2 + base; const h16* Bv = LAB + (size_t)3 * CT * D + base;
;       float2 cr = *(const float2*)(CARRY + (size_t)(256 + seg) * D + c2); float h0 = cr.x, h1 = cr.y;
; #pragma unroll 1
;       for (int tb = 56; tb >= 0; tb -= 8) {
;         unsigned short la[8]; h16x2 bb[8]; unsigned yp[8], ym[8], g0[8], g1[8], g2[8];
; #pragma unroll
;         for (int i = 0; i < 8; ++i) { const int t = tb + i;
;           la[i] = NT_LOAD((const unsigned short*)(LA + (size_t)t * D)); bb[i] = NT_LOAD((const h16x2*)(Bv + (size_t)t * D));
;           const bf16* zr = Z + ((size_t)seg * 64 + t) * DIN + c2;
;           yp[i] = NT_LOAD((const unsigned*)zr); ym[i] = NT_LOAD((const unsigned*)(zr + 1024));
;           const unsigned char* gz = (const unsigned char*)(Z + ((size_t)seg * 64 + t) * DIN) + 6144 + c2;
;           g0[i] = NT_LOAD((const unsigned short*)gz); g1[i] = NT_LOAD((const unsigned short*)(gz + 1024)); g2[i] = NT_LOAD((const unsigned short*)(gz + 2048)); }
	v_cvt_f32_ubyte0_e32 v17, v54
	v_mul_f32_e32 v17, v22, v17
	v_mul_f32_e32 v17, s100, v17
	v_exp_f32_e32 v32, v17
	v_pk_mul_f32 v[18:19], v[30:31], v[18:19]
	v_fma_f32 v17, -v32, v32, 1.0
	v_max_f32_e32 v17, 0, v17
	v_sqrt_f32_e32 v34, v17
	v_cvt_f32_ubyte1_e32 v17, v54
	v_mul_f32_e32 v17, v23, v17
	v_mul_f32_e32 v17, s100, v17
	v_exp_f32_e32 v33, v17
	s_nop 0
	v_fma_f32 v17, -v33, v33, 1.0
	v_max_f32_e32 v17, 0, v17
	v_sqrt_f32_e32 v35, v17
	s_waitcnt vmcnt(5)
	v_cvt_f32_ubyte0_e32 v17, v56
	v_mul_f32_e32 v17, v22, v17
	v_mul_f32_e32 v17, s100, v17
	v_exp_f32_e32 v36, v17
	s_nop 0
	v_fma_f32 v17, -v36, v36, 1.0
	v_max_f32_e32 v17, 0, v17
	v_sqrt_f32_e32 v38, v17
	v_cvt_f32_ubyte1_e32 v17, v56
	v_mul_f32_e32 v17, v23, v17
	v_mul_f32_e32 v17, s100, v17
	v_exp_f32_e32 v37, v17
	s_nop 0
	v_fma_f32 v17, -v37, v37, 1.0
	v_max_f32_e32 v17, 0, v17
	v_sqrt_f32_e32 v39, v17
	s_waitcnt vmcnt(3)
	v_cvt_f32_ubyte0_e32 v17, v58
	v_mul_f32_e32 v17, v22, v17
	v_mul_f32_e32 v17, s100, v17
	v_exp_f32_e32 v40, v17
	s_nop 0
	v_fma_f32 v17, -v40, v40, 1.0
	v_max_f32_e32 v17, 0, v17
	v_sqrt_f32_e32 v42, v17
	v_cvt_f32_ubyte1_e32 v17, v58
	v_mul_f32_e32 v17, v23, v17
	v_mul_f32_e32 v17, s100, v17
	v_exp_f32_e32 v41, v17
	s_nop 0
	v_fma_f32 v17, -v41, v41, 1.0
	v_max_f32_e32 v17, 0, v17
	v_sqrt_f32_e32 v43, v17
	s_waitcnt vmcnt(1)
	v_cvt_f32_ubyte0_e32 v17, v60
	v_mul_f32_e32 v17, v22, v17
	v_mul_f32_e32 v17, s100, v17
	v_exp_f32_e32 v44, v17
	s_nop 0
	v_fma_f32 v17, -v44, v44, 1.0
	v_max_f32_e32 v17, 0, v17
	v_sqrt_f32_e32 v46, v17
	v_cvt_f32_ubyte1_e32 v17, v60
	v_mul_f32_e32 v17, v23, v17
	v_mul_f32_e32 v17, s100, v17
	v_exp_f32_e32 v45, v17
	s_nop 0
	v_fma_f32 v17, -v45, v45, 1.0
	v_max_f32_e32 v17, 0, v17
	v_sqrt_f32_e32 v47, v17
	v_cvt_pk_f16_f32 v17, v14, v15
	v_pk_fma_f32 v[14:15], v[28:29], v[14:15], v[18:19]
	v_cvt_f32_f16_sdwa v19, v55 dst_sel:DWORD dst_unused:UNUSED_PAD src0_sel:WORD_1
	v_cvt_pk_f16_f32 v18, v14, v15
	ds_write2st64_b32 v16, v17, v18 offset0:80 offset1:88
	v_cvt_f32_f16_e32 v18, v55
	v_pk_mul_f32 v[18:19], v[34:35], v[18:19]
	s_nop 0
	v_pk_fma_f32 v[14:15], v[32:33], v[14:15], v[18:19]
	v_cvt_f32_f16_e32 v18, v57
	v_cvt_f32_f16_sdwa v19, v57 dst_sel:DWORD dst_unused:UNUSED_PAD src0_sel:WORD_1
	v_cvt_pk_f16_f32 v17, v14, v15
	v_pk_mul_f32 v[18:19], v[38:39], v[18:19]
	s_nop 0
	v_pk_fma_f32 v[14:15], v[36:37], v[14:15], v[18:19]
	v_cvt_f32_f16_sdwa v19, v59 dst_sel:DWORD dst_unused:UNUSED_PAD src0_sel:WORD_1
	v_cvt_pk_f16_f32 v18, v14, v15
	ds_write2st64_b32 v16, v17, v18 offset0:96 offset1:104
	v_cvt_f32_f16_e32 v18, v59
	v_pk_mul_f32 v[18:19], v[42:43], v[18:19]
	s_nop 0
	v_pk_fma_f32 v[14:15], v[40:41], v[14:15], v[18:19]
	s_waitcnt vmcnt(0)
	v_cvt_f32_f16_e32 v18, v61
	v_cvt_f32_f16_sdwa v19, v61 dst_sel:DWORD dst_unused:UNUSED_PAD src0_sel:WORD_1
	v_cvt_pk_f16_f32 v17, v14, v15
	v_pk_mul_f32 v[18:19], v[46:47], v[18:19]
	s_nop 0
	v_pk_fma_f32 v[14:15], v[44:45], v[14:15], v[18:19]
	s_nop 0
	v_cvt_pk_f16_f32 v18, v14, v15
	ds_write2st64_b32 v16, v17, v18 offset0:112 offset1:120
	v_add_u32_e32 v16, 0x8000, v16
	s_cbranch_scc1 .LBB0_59
	s_lshl_b64 s[16:17], s[8:9], 12
	v_lshl_add_u64 v[10:11], v[2:3], 0, s[16:17]
	v_add_co_u32_e32 v10, vcc, 0x100000, v10
	v_mad_i64_i32 v[12:13], s[16:17], s8, v190, v[4:5]
	s_nop 0
	v_addc_co_u32_e32 v11, vcc, 0, v11, vcc
	global_load_dwordx2 v[14:15], v[10:11], off
	v_mad_i64_i32 v[10:11], s[16:17], s8, v190, v[0:1]
	s_mov_b32 s9, 0
.LBB0_61:
	s_mov_b32 s100, 0x3fb8aa3b
	s_mov_b32 s101, 0xffff0000
	v_lshl_add_u64 v[18:19], s[4:5], 0, v[8:9]
	v_add_co_u32_e32 v20, vcc, 0xda0e000, v18
	v_lshl_add_u64 v[16:17], s[4:5], 0, v[6:7]
	s_nop 0
	v_addc_co_u32_e32 v21, vcc, 0, v19, vcc
	v_add_co_u32_e32 v34, vcc, 0xfa1c000, v16
	v_lshl_add_u64 v[80:81], s[4:5], 0, v[12:13]
	s_nop 0
	v_addc_co_u32_e32 v35, vcc, 0, v17, vcc
	v_add_co_u32_e32 v30, vcc, 0x11aa8000, v80
	v_lshl_add_u64 v[82:83], s[4:5], 0, v[10:11]
	s_nop 0
	v_addc_co_u32_e32 v31, vcc, 0, v81, vcc
	global_load_ushort v37, v[20:21], off nt
	global_load_dword v27, v[34:35], off nt
	global_load_dword v28, v[30:31], off nt
	global_load_dword v29, v[30:31], off offset:2048 nt
	v_add_co_u32_e32 v30, vcc, 0x11aa9000, v82
	v_add_u32_e32 v94, s9, v26
	s_nop 0
	v_addc_co_u32_e32 v31, vcc, 0, v83, vcc
	v_add_co_u32_e32 v38, vcc, 0x11aaa000, v82
	global_load_ushort v32, v[30:31], off offset:2048 nt
	s_nop 0
	global_load_ushort v31, v[30:31], off offset:3072 nt
	v_addc_co_u32_e32 v39, vcc, 0, v83, vcc
	global_load_ushort v30, v[38:39], off nt
	global_load_ushort v48, v[20:21], off offset:1024 nt
	global_load_dword v33, v[34:35], off offset:2048 nt
	v_add_co_u32_e32 v34, vcc, 0x11aab000, v80
	v_add_u32_e32 v100, 0x1c000, v94
	s_nop 0
	v_addc_co_u32_e32 v35, vcc, 0, v81, vcc
	global_load_dword v46, v[34:35], off nt
	global_load_dword v47, v[34:35], off offset:2048 nt
	v_add_co_u32_e32 v34, vcc, 0x11aac000, v82
	s_mov_b32 s16, 0x5a1c000
	s_nop 0
	v_addc_co_u32_e32 v35, vcc, 0, v83, vcc
	v_add_co_u32_e32 v38, vcc, 0x11aad000, v82
	global_load_ushort v36, v[34:35], off offset:2048 nt
	s_nop 0
	global_load_ushort v34, v[34:35], off offset:3072 nt
	v_addc_co_u32_e32 v39, vcc, 0, v83, vcc
	v_add_co_u32_e32 v42, vcc, 0xfa1d000, v16
	global_load_ushort v35, v[38:39], off nt
	global_load_ushort v55, v[20:21], off offset:2048 nt
	v_addc_co_u32_e32 v43, vcc, 0, v17, vcc
	v_add_co_u32_e32 v40, vcc, 0x11aae000, v80
	global_load_dword v38, v[42:43], off nt
	s_nop 0
	v_addc_co_u32_e32 v41, vcc, 0, v81, vcc
	v_add_co_u32_e32 v44, vcc, 0x11aaf000, v82
	global_load_dword v53, v[40:41], off nt
	global_load_dword v54, v[40:41], off offset:2048 nt
	v_addc_co_u32_e32 v45, vcc, 0, v83, vcc
; #define NT_LOAD(p) __builtin_nontemporal_load(p)
; __device__ __forceinline__ float lru_step(float la, float bx, float h) { float a = __expf(la); return a * h + __builtin_amdgcn_sqrtf(fmaxf(1.f - a * a, 0.f)) * bx; }
; __device__ __forceinline__ void phase4c(KP pp, int l) {
;     ...
;         for (int i = 0; i < 8; ++i) { const int t = tb + i;
;           la[i] = NT_LOAD((const unsigned short*)(LA + (size_t)t * D)); bb[i] = NT_LOAD((const h16x2*)(Bv + (size_t)t * D));
;           const bf16* zr = Z + ((size_t)seg * 64 + t) * DIN + c2;
;           yp[i] = NT_LOAD((const unsigned*)zr); ym[i] = NT_LOAD((const unsigned*)(zr + 1024));
;           const unsigned char* gz = (const unsigned char*)(Z + ((size_t)seg * 64 + t) * DIN) + 6144 + c2;
;           g0[i] = NT_LOAD((const unsigned short*)gz); g1[i] = NT_LOAD((const unsigned short*)(gz + 1024)); g2[i] = NT_LOAD((const unsigned short*)(gz + 2048)); }
;         unsigned outw[8];
; #pragma unroll
;         for (int i = 7; i >= 0; --i) { const int t = tb + i;
;           h0 = lru_step(kb0 * (float)(la[i] & 255), (float)bb[i][0], h0); h1 = lru_step(kb1 * (float)(la[i] >> 8), (float)bb[i][1], h1);
;           h16x2 f = hf[t * 512 + tid_];
;           float yl0 = (float)f[0] + h0, yl1 = (float)f[1] + h1;
;           const float k255 = 1.f / 255.f;
;           float m0 = (float)(g0[i] & 255u) * k255 * bflo(yp[i]) + (float)(g1[i] & 255u) * k255 * yl0 + (float)(g2[i] & 255u) * k255 * bflo(ym[i]);
;           float m1 = (float)(g0[i] >> 8) * k255 * bfhi(yp[i]) + (float)(g1[i] >> 8) * k255 * yl1 + (float)(g2[i] >> 8) * k255 * bfhi(ym[i]);
	global_load_ushort v41, v[44:45], off offset:2048 nt
	global_load_ushort v39, v[44:45], off offset:3072 nt
	v_add_co_u32_e32 v44, vcc, 0x11ab0000, v82
	s_addk_i32 s9, 0xc000
	s_nop 0
	v_addc_co_u32_e32 v45, vcc, 0, v83, vcc
	global_load_ushort v40, v[44:45], off nt
	global_load_ushort v61, v[20:21], off offset:3072 nt
	s_nop 0
	global_load_dword v42, v[42:43], off offset:2048 nt
	v_add_co_u32_e32 v20, vcc, 0x11ab1000, v80
	v_lshl_add_u64 v[10:11], v[10:11], 0, s[48:49]
	s_nop 0
	v_addc_co_u32_e32 v21, vcc, 0, v81, vcc
	global_load_dword v59, v[20:21], off nt
	global_load_dword v60, v[20:21], off offset:2048 nt
	v_add_co_u32_e32 v20, vcc, 0x11ab2000, v82
	v_lshl_add_u64 v[12:13], v[12:13], 0, s[48:49]
	s_nop 0
	v_addc_co_u32_e32 v21, vcc, 0, v83, vcc
	global_load_ushort v45, v[20:21], off offset:2048 nt
	global_load_ushort v43, v[20:21], off offset:3072 nt
	v_add_co_u32_e32 v20, vcc, 0x11ab3000, v82
	v_lshl_add_u64 v[6:7], v[6:7], 0, s[46:47]
	s_nop 0
	v_addc_co_u32_e32 v21, vcc, 0, v83, vcc
	v_add_co_u32_e32 v18, vcc, 0xda0f000, v18
	global_load_ushort v44, v[20:21], off nt
	s_nop 0
	v_addc_co_u32_e32 v19, vcc, 0, v19, vcc
	global_load_ushort v64, v[18:19], off nt
	v_add_co_u32_e32 v20, vcc, 0xfa1e000, v16
	s_cmp_eq_u32 s9, 0xfffe0000
	s_nop 0
	v_addc_co_u32_e32 v21, vcc, 0, v17, vcc
	v_add_co_u32_e32 v50, vcc, 0x11ab4000, v80
	global_load_dword v49, v[20:21], off nt
	s_nop 0
	v_addc_co_u32_e32 v51, vcc, 0, v81, vcc
	global_load_dword v62, v[50:51], off nt
	global_load_dword v63, v[50:51], off offset:2048 nt
	v_add_co_u32_e32 v50, vcc, 0x11ab5000, v82
	s_nop 1
	v_addc_co_u32_e32 v51, vcc, 0, v83, vcc
	v_add_co_u32_e32 v56, vcc, 0x11ab6000, v82
	global_load_ushort v52, v[50:51], off offset:2048 nt
	s_nop 0
	global_load_ushort v50, v[50:51], off offset:3072 nt
	v_addc_co_u32_e32 v57, vcc, 0, v83, vcc
	global_load_ushort v51, v[56:57], off nt
	global_load_ushort v72, v[18:19], off offset:1024 nt
	global_load_dword v67, v[20:21], off offset:2048 nt
	v_add_co_u32_e32 v20, vcc, 0x11ab7000, v80
	s_nop 1
	v_addc_co_u32_e32 v21, vcc, 0, v81, vcc
	global_load_dword v65, v[20:21], off nt
	global_load_dword v66, v[20:21], off offset:2048 nt
	v_add_co_u32_e32 v20, vcc, 0x11ab8000, v82
	s_nop 1
	v_addc_co_u32_e32 v21, vcc, 0, v83, vcc
	global_load_ushort v58, v[20:21], off offset:2048 nt
	global_load_ushort v56, v[20:21], off offset:3072 nt
	v_add_co_u32_e32 v20, vcc, 0x11ab9000, v82
	s_nop 1
	v_addc_co_u32_e32 v21, vcc, 0, v83, vcc
	global_load_ushort v57, v[20:21], off nt
	global_load_ushort v79, v[18:19], off offset:2048 nt
	v_add_co_u32_e32 v20, vcc, 0xfa1f000, v16
	s_waitcnt vmcnt(1)
	v_cvt_f32_ubyte1_e32 v99, v57
	v_addc_co_u32_e32 v21, vcc, 0, v17, vcc
	v_add_co_u32_e32 v70, vcc, 0x11aba000, v80
	global_load_dword v68, v[20:21], off nt
	s_nop 0
	v_addc_co_u32_e32 v71, vcc, 0, v81, vcc
	v_add_co_u32_e32 v84, vcc, 0x11abb000, v82
	global_load_dword v75, v[70:71], off nt
	global_load_dword v76, v[70:71], off offset:2048 nt
	v_addc_co_u32_e32 v85, vcc, 0, v83, vcc
	global_load_ushort v71, v[84:85], off offset:2048 nt
	global_load_ushort v69, v[84:85], off offset:3072 nt
	v_add_co_u32_e32 v84, vcc, 0x11abc000, v82
	s_waitcnt vmcnt(3)
	v_lshlrev_b32_e32 v88, 16, v75
	v_addc_co_u32_e32 v85, vcc, 0, v83, vcc
	global_load_ushort v70, v[84:85], off nt
	s_nop 0
	global_load_ushort v84, v[18:19], off offset:3072 nt
	global_load_dword v73, v[20:21], off offset:2048 nt
	v_add_co_u32_e32 v18, vcc, 0x11abd000, v80
	v_and_b32_e32 v89, s101, v75
	s_nop 0
	v_addc_co_u32_e32 v19, vcc, 0, v81, vcc
	global_load_dword v80, v[18:19], off nt
	global_load_dword v81, v[18:19], off offset:2048 nt
	v_add_co_u32_e32 v18, vcc, 0x11abe000, v82
	v_cvt_f32_ubyte0_e32 v75, v72
	s_nop 0
	v_addc_co_u32_e32 v19, vcc, 0, v83, vcc
	global_load_ushort v78, v[18:19], off offset:2048 nt
	global_load_ushort v74, v[18:19], off offset:3072 nt
	v_add_co_u32_e32 v18, vcc, 0x11abf000, v82
	v_add_u32_e32 v82, 0x1f800, v94
	s_nop 0
	v_addc_co_u32_e32 v19, vcc, 0, v83, vcc
	global_load_ushort v77, v[18:19], off nt
	ds_read_b32 v95, v82
	v_cvt_f32_ubyte1_e32 v72, v72
	v_mul_f32_e32 v72, v25, v72
	v_mul_f32_e32 v72, s100, v72
	v_exp_f32_e32 v93, v72
	v_mul_f32_e32 v75, v24, v75
	v_mul_f32_e32 v75, s100, v75
	v_exp_f32_e32 v92, v75
	s_waitcnt vmcnt(10)
	v_lshlrev_b32_e32 v90, 16, v76
	v_and_b32_e32 v91, s101, v76
	v_fma_f32 v75, -v92, v92, 1.0
	v_max_f32_e32 v75, 0, v75
	v_sqrt_f32_e32 v76, v75
	s_waitcnt vmcnt(6)
	v_cvt_f32_ubyte0_e32 v18, v84
	v_mul_f32_e32 v18, v24, v18
	v_mul_f32_e32 v18, s100, v18
	v_exp_f32_e32 v18, v18
	s_waitcnt vmcnt(5)
	v_cvt_f32_f16_e32 v72, v73
	v_cvt_f32_f16_sdwa v73, v73 dst_sel:DWORD dst_unused:UNUSED_PAD src0_sel:WORD_1
	s_waitcnt vmcnt(4)
	v_lshlrev_b32_e32 v82, 16, v80
	v_fma_f32 v19, -v18, v18, 1.0
	v_max_f32_e32 v19, 0, v19
	v_sqrt_f32_e32 v20, v19
	v_cvt_f32_ubyte1_e32 v19, v84
	v_mul_f32_e32 v19, v25, v19
	v_mul_f32_e32 v19, s100, v19
	v_exp_f32_e32 v19, v19
	v_and_b32_e32 v83, s101, v80
	v_cvt_f32_ubyte0_e32 v80, v79
	v_mul_f32_e32 v80, v24, v80
	v_mul_f32_e32 v80, s100, v80
	v_exp_f32_e32 v80, v80
	v_fma_f32 v21, -v19, v19, 1.0
	v_max_f32_e32 v21, 0, v21
	v_sqrt_f32_e32 v21, v21
	v_cvt_f32_ubyte1_e32 v79, v79
	s_waitcnt vmcnt(3)
	v_lshlrev_b32_e32 v84, 16, v81
	v_and_b32_e32 v85, s101, v81
	v_fma_f32 v81, -v80, v80, 1.0
	v_mul_f32_e32 v79, v25, v79
	v_max_f32_e32 v81, 0, v81
	v_mul_f32_e32 v79, s100, v79
	v_sqrt_f32_e32 v86, v81
	v_exp_f32_e32 v81, v79
	v_pk_mul_f32 v[20:21], v[20:21], v[72:73]
	s_waitcnt vmcnt(1)
	v_cvt_f32_ubyte1_e32 v73, v74
	v_pk_fma_f32 v[14:15], v[14:15], v[18:19], v[20:21]
	s_waitcnt lgkmcnt(0)
; __device__ __forceinline__ unsigned pk2(float lo, float hi) { f32x2 v = {lo, hi}; return __builtin_bit_cast(unsigned, __builtin_convertvector(v, hwbf16x2)); }
; __device__ __forceinline__ float lru_step(float la, float bx, float h) { float a = __expf(la); return a * h + __builtin_amdgcn_sqrtf(fmaxf(1.f - a * a, 0.f)) * bx; }
; __device__ __forceinline__ void phase4c(KP pp, int l) {
;     ...
;         for (int i = 7; i >= 0; --i) { const int t = tb + i;
;           h0 = lru_step(kb0 * (float)(la[i] & 255), (float)bb[i][0], h0); h1 = lru_step(kb1 * (float)(la[i] >> 8), (float)bb[i][1], h1);
;           h16x2 f = hf[t * 512 + tid_];
;           float yl0 = (float)f[0] + h0, yl1 = (float)f[1] + h1;
;           const float k255 = 1.f / 255.f;
;           float m0 = (float)(g0[i] & 255u) * k255 * bflo(yp[i]) + (float)(g1[i] & 255u) * k255 * yl0 + (float)(g2[i] & 255u) * k255 * bflo(ym[i]);
;           float m1 = (float)(g0[i] >> 8) * k255 * bfhi(yp[i]) + (float)(g1[i] >> 8) * k255 * yl1 + (float)(g2[i] >> 8) * k255 * bfhi(ym[i]);
;           outw[i] = pk2(m0, m1); }
	v_cvt_f32_f16_e32 v18, v95
	v_cvt_f32_f16_sdwa v19, v95 dst_sel:DWORD dst_unused:UNUSED_PAD src0_sel:WORD_1
	v_fma_f32 v79, -v81, v81, 1.0
	v_max_f32_e32 v79, 0, v79
	v_cvt_f32_ubyte0_e32 v72, v74
	v_sqrt_f32_e32 v87, v79
	v_add_u32_e32 v79, 0x1f000, v94
	v_cvt_f32_ubyte1_e32 v21, v78
	v_cvt_f32_ubyte0_e32 v20, v78
	v_pk_mul_f32 v[72:73], v[72:73], s[52:53] op_sel_hi:[1,0]
	v_pk_add_f32 v[18:19], v[14:15], v[18:19]
	ds_read_b32 v79, v79
	v_pk_mul_f32 v[20:21], v[20:21], s[52:53] op_sel_hi:[1,0]
	v_pk_mul_f32 v[18:19], v[72:73], v[18:19]
	v_pk_mul_f32 v[14:15], v[80:81], v[14:15]
	v_pk_fma_f32 v[18:19], v[20:21], v[82:83], v[18:19]
	v_cvt_f32_f16_e32 v20, v68
	v_cvt_f32_f16_sdwa v21, v68 dst_sel:DWORD dst_unused:UNUSED_PAD src0_sel:WORD_1
	s_waitcnt vmcnt(0)
	v_cvt_f32_ubyte1_e32 v75, v77
	v_cvt_f32_ubyte0_e32 v74, v77
	v_pk_mul_f32 v[74:75], v[74:75], s[52:53] op_sel_hi:[1,0]
	v_pk_fma_f32 v[14:15], v[86:87], v[20:21], v[14:15]
	s_waitcnt lgkmcnt(0)
	v_cvt_f32_f16_e32 v20, v79
	v_cvt_f32_f16_sdwa v21, v79 dst_sel:DWORD dst_unused:UNUSED_PAD src0_sel:WORD_1
	v_pk_fma_f32 v[18:19], v[74:75], v[84:85], v[18:19]
	v_cvt_f32_ubyte1_e32 v75, v69
	v_cvt_f32_ubyte0_e32 v74, v69
	v_cvt_f32_ubyte1_e32 v73, v71
	v_cvt_f32_ubyte0_e32 v72, v71
	v_pk_mul_f32 v[68:69], v[74:75], s[52:53] op_sel_hi:[1,0]
	v_pk_add_f32 v[20:21], v[14:15], v[20:21]
	v_pk_mul_f32 v[72:73], v[72:73], s[52:53] op_sel_hi:[1,0]
	v_cvt_f32_ubyte1_e32 v71, v70
	v_cvt_f32_ubyte0_e32 v70, v70
	v_pk_mul_f32 v[20:21], v[68:69], v[20:21]
	v_pk_mul_f32 v[70:71], v[70:71], s[52:53] op_sel_hi:[1,0]
	v_pk_fma_f32 v[20:21], v[72:73], v[88:89], v[20:21]
	v_cvt_pk_bf16_f32 v18, v18, v19
	v_pk_fma_f32 v[20:21], v[70:71], v[90:91], v[20:21]
	v_lshlrev_b32_e32 v68, 16, v65
	v_cvt_pk_bf16_f32 v19, v20, v21
	v_fma_f32 v20, -v93, v93, 1.0
	v_and_b32_e32 v69, s101, v65
	v_cvt_f32_ubyte0_e32 v65, v64
	v_cvt_f32_ubyte1_e32 v64, v64
	v_max_f32_e32 v20, 0, v20
	v_mul_f32_e32 v64, v25, v64
	v_sqrt_f32_e32 v77, v20
	v_cvt_f32_f16_e32 v20, v67
	v_cvt_f32_f16_sdwa v21, v67 dst_sel:DWORD dst_unused:UNUSED_PAD src0_sel:WORD_1
	v_add_u32_e32 v67, 0x1e800, v94
	v_mul_f32_e32 v65, v24, v65
	v_mul_f32_e32 v64, s100, v64
	ds_read_b32 v98, v67
	v_mul_f32_e32 v65, s100, v65
	v_exp_f32_e32 v67, v64
	v_lshlrev_b32_e32 v70, 16, v66
	v_and_b32_e32 v71, s101, v66
	v_exp_f32_e32 v66, v65
	v_fma_f32 v64, -v67, v67, 1.0
	v_max_f32_e32 v64, 0, v64
	v_sqrt_f32_e32 v73, v64
	v_fma_f32 v65, -v66, v66, 1.0
	v_max_f32_e32 v65, 0, v65
	v_add_u32_e32 v64, 0x1e000, v94
	v_sqrt_f32_e32 v72, v65
	ds_read_b32 v101, v64
	v_lshlrev_b32_e32 v64, 16, v62
	v_and_b32_e32 v65, s101, v62
	v_cvt_f32_ubyte0_e32 v62, v61
	v_mul_f32_e32 v62, v24, v62
	v_mul_f32_e32 v62, s100, v62
	v_exp_f32_e32 v62, v62
	v_cvt_f32_ubyte1_e32 v61, v61
	v_lshlrev_b32_e32 v74, 16, v63
	v_and_b32_e32 v75, s101, v63
	v_fma_f32 v63, -v62, v62, 1.0
	v_mul_f32_e32 v61, v25, v61
	v_max_f32_e32 v63, 0, v63
	v_mul_f32_e32 v61, s100, v61
	v_sqrt_f32_e32 v78, v63
	v_exp_f32_e32 v63, v61
	v_lshlrev_b32_e32 v80, 16, v59
	v_and_b32_e32 v81, s101, v59
	v_cvt_f32_ubyte0_e32 v59, v55
	v_mul_f32_e32 v59, v24, v59
	v_mul_f32_e32 v59, s100, v59
	v_fma_f32 v61, -v63, v63, 1.0
	v_lshlrev_b32_e32 v82, 16, v60
	v_and_b32_e32 v83, s101, v60
	v_exp_f32_e32 v60, v59
	v_cvt_f32_ubyte1_e32 v55, v55
	v_pk_mul_f32 v[14:15], v[92:93], v[14:15]
	v_max_f32_e32 v61, 0, v61
	v_mul_f32_e32 v55, v25, v55
	v_sqrt_f32_e32 v79, v61
	v_add_u32_e32 v61, 0x1d800, v94
	v_mul_f32_e32 v55, s100, v55
	v_pk_fma_f32 v[14:15], v[76:77], v[20:21], v[14:15]
	s_waitcnt lgkmcnt(1)
	v_cvt_f32_f16_e32 v20, v98
	v_cvt_f32_f16_sdwa v21, v98 dst_sel:DWORD dst_unused:UNUSED_PAD src0_sel:WORD_1
	ds_read_b32 v102, v61
	v_exp_f32_e32 v61, v55
	v_fma_f32 v59, -v60, v60, 1.0
	v_max_f32_e32 v59, 0, v59
	v_cvt_f32_ubyte1_e32 v77, v56
	v_cvt_f32_ubyte0_e32 v76, v56
	v_sqrt_f32_e32 v84, v59
	v_cvt_f32_ubyte1_e32 v59, v58
	v_cvt_f32_ubyte0_e32 v58, v58
	v_pk_mul_f32 v[76:77], v[76:77], s[52:53] op_sel_hi:[1,0]
	v_pk_add_f32 v[20:21], v[14:15], v[20:21]
	v_fma_f32 v55, -v61, v61, 1.0
	v_lshlrev_b32_e32 v86, 16, v53
	v_and_b32_e32 v87, s101, v53
	v_cvt_f32_ubyte0_e32 v53, v48
	v_cvt_f32_ubyte1_e32 v48, v48
	v_pk_mul_f32 v[58:59], v[58:59], s[52:53] op_sel_hi:[1,0]
	v_cvt_f32_ubyte0_e32 v98, v57
	v_pk_mul_f32 v[20:21], v[76:77], v[20:21]
	v_max_f32_e32 v55, 0, v55
	v_mul_f32_e32 v48, v25, v48
	v_pk_mul_f32 v[56:57], v[98:99], s[52:53] op_sel_hi:[1,0]
	v_pk_fma_f32 v[20:21], v[58:59], v[68:69], v[20:21]
	v_sqrt_f32_e32 v85, v55
	v_add_u32_e32 v55, 0x1d000, v94
	v_mul_f32_e32 v53, v24, v53
	v_mul_f32_e32 v48, s100, v48
	v_pk_fma_f32 v[20:21], v[56:57], v[70:71], v[20:21]
	ds_read_b32 v103, v55
	v_mul_f32_e32 v53, s100, v53
	v_exp_f32_e32 v55, v48
	v_cvt_pk_bf16_f32 v58, v20, v21
	v_cvt_f32_f16_e32 v20, v49
	v_cvt_f32_f16_sdwa v21, v49 dst_sel:DWORD dst_unused:UNUSED_PAD src0_sel:WORD_1
	v_lshlrev_b32_e32 v88, 16, v54
	v_and_b32_e32 v89, s101, v54
	v_exp_f32_e32 v54, v53
	v_pk_mul_f32 v[14:15], v[66:67], v[14:15]
	v_fma_f32 v48, -v55, v55, 1.0
	v_pk_fma_f32 v[14:15], v[72:73], v[20:21], v[14:15]
	s_waitcnt lgkmcnt(2)
; __device__ __forceinline__ unsigned pk2(float lo, float hi) { f32x2 v = {lo, hi}; return __builtin_bit_cast(unsigned, __builtin_convertvector(v, hwbf16x2)); }
; __device__ __forceinline__ float lru_step(float la, float bx, float h) { float a = __expf(la); return a * h + __builtin_amdgcn_sqrtf(fmaxf(1.f - a * a, 0.f)) * bx; }
; __device__ __forceinline__ void phase4c(KP pp, int l) {
;     ...
;         for (int i = 7; i >= 0; --i) { const int t = tb + i;
;           h0 = lru_step(kb0 * (float)(la[i] & 255), (float)bb[i][0], h0); h1 = lru_step(kb1 * (float)(la[i] >> 8), (float)bb[i][1], h1);
;           h16x2 f = hf[t * 512 + tid_];
;           float yl0 = (float)f[0] + h0, yl1 = (float)f[1] + h1;
;           const float k255 = 1.f / 255.f;
;           float m0 = (float)(g0[i] & 255u) * k255 * bflo(yp[i]) + (float)(g1[i] & 255u) * k255 * yl0 + (float)(g2[i] & 255u) * k255 * bflo(ym[i]);
;           float m1 = (float)(g0[i] >> 8) * k255 * bfhi(yp[i]) + (float)(g1[i] >> 8) * k255 * yl1 + (float)(g2[i] >> 8) * k255 * bfhi(ym[i]);
;           outw[i] = pk2(m0, m1); }
; #pragma unroll
;         for (int i = 0; i < 8; ++i) *(unsigned*)(MERGED + ((size_t)seg * 64 + tb + i) * D + c2) = outw[i];
;       } }
;     __syncthreads();
	v_cvt_f32_f16_e32 v20, v101
	v_cvt_f32_f16_sdwa v21, v101 dst_sel:DWORD dst_unused:UNUSED_PAD src0_sel:WORD_1
	v_fma_f32 v53, -v54, v54, 1.0
	v_max_f32_e32 v48, 0, v48
	v_max_f32_e32 v53, 0, v53
	v_sqrt_f32_e32 v91, v48
	v_add_u32_e32 v48, 0x1c800, v94
	v_sqrt_f32_e32 v90, v53
	ds_read_b32 v104, v48
	v_cvt_f32_ubyte1_e32 v49, v52
	v_cvt_f32_ubyte0_e32 v48, v52
	v_cvt_f32_ubyte1_e32 v53, v50
	v_cvt_f32_ubyte0_e32 v52, v50
	v_pk_mul_f32 v[52:53], v[52:53], s[52:53] op_sel_hi:[1,0]
	v_pk_add_f32 v[20:21], v[14:15], v[20:21]
	v_pk_mul_f32 v[48:49], v[48:49], s[52:53] op_sel_hi:[1,0]
	v_cvt_f32_ubyte1_e32 v57, v51
	v_cvt_f32_ubyte0_e32 v56, v51
	v_pk_mul_f32 v[20:21], v[52:53], v[20:21]
	v_pk_mul_f32 v[50:51], v[56:57], s[52:53] op_sel_hi:[1,0]
	v_pk_fma_f32 v[20:21], v[48:49], v[64:65], v[20:21]
	v_pk_mul_f32 v[14:15], v[62:63], v[14:15]
	v_pk_fma_f32 v[20:21], v[50:51], v[74:75], v[20:21]
	v_cvt_f32_ubyte1_e32 v51, v43
	v_cvt_pk_bf16_f32 v52, v20, v21
	v_cvt_f32_f16_e32 v20, v42
	v_cvt_f32_f16_sdwa v21, v42 dst_sel:DWORD dst_unused:UNUSED_PAD src0_sel:WORD_1
	v_cvt_f32_ubyte0_e32 v50, v43
	v_cvt_f32_ubyte1_e32 v49, v45
	v_cvt_f32_ubyte0_e32 v48, v45
	v_pk_fma_f32 v[14:15], v[78:79], v[20:21], v[14:15]
	s_waitcnt lgkmcnt(2)
	v_cvt_f32_f16_e32 v20, v102
	v_cvt_f32_f16_sdwa v21, v102 dst_sel:DWORD dst_unused:UNUSED_PAD src0_sel:WORD_1
	v_pk_mul_f32 v[42:43], v[50:51], s[52:53] op_sel_hi:[1,0]
	v_pk_mul_f32 v[48:49], v[48:49], s[52:53] op_sel_hi:[1,0]
	v_cvt_f32_ubyte1_e32 v45, v44
	v_pk_add_f32 v[20:21], v[14:15], v[20:21]
	v_cvt_f32_ubyte0_e32 v44, v44
	v_pk_mul_f32 v[20:21], v[42:43], v[20:21]
	v_pk_mul_f32 v[44:45], v[44:45], s[52:53] op_sel_hi:[1,0]
	v_pk_fma_f32 v[20:21], v[48:49], v[80:81], v[20:21]
	v_pk_mul_f32 v[14:15], v[60:61], v[14:15]
	v_pk_fma_f32 v[20:21], v[44:45], v[82:83], v[20:21]
	v_lshlrev_b32_e32 v92, 16, v46
	v_cvt_pk_bf16_f32 v48, v20, v21
	v_cvt_f32_f16_e32 v20, v38
	v_cvt_f32_f16_sdwa v21, v38 dst_sel:DWORD dst_unused:UNUSED_PAD src0_sel:WORD_1
	v_and_b32_e32 v93, s101, v46
	v_cvt_f32_ubyte0_e32 v46, v37
	v_mul_f32_e32 v46, v24, v46
	v_pk_fma_f32 v[14:15], v[84:85], v[20:21], v[14:15]
	s_waitcnt lgkmcnt(1)
	v_cvt_f32_f16_e32 v20, v103
	v_cvt_f32_f16_sdwa v21, v103 dst_sel:DWORD dst_unused:UNUSED_PAD src0_sel:WORD_1
	v_mul_f32_e32 v46, s100, v46
	v_cvt_f32_ubyte1_e32 v45, v39
	v_cvt_f32_ubyte0_e32 v44, v39
	v_exp_f32_e32 v46, v46
	v_cvt_f32_ubyte1_e32 v43, v41
	v_cvt_f32_ubyte0_e32 v42, v41
	v_pk_mul_f32 v[38:39], v[44:45], s[52:53] op_sel_hi:[1,0]
	v_pk_add_f32 v[20:21], v[14:15], v[20:21]
	v_pk_mul_f32 v[42:43], v[42:43], s[52:53] op_sel_hi:[1,0]
	v_cvt_f32_ubyte1_e32 v41, v40
	v_cvt_f32_ubyte0_e32 v40, v40
	v_pk_mul_f32 v[20:21], v[38:39], v[20:21]
	v_pk_mul_f32 v[40:41], v[40:41], s[52:53] op_sel_hi:[1,0]
	v_pk_fma_f32 v[20:21], v[42:43], v[86:87], v[20:21]
	v_cvt_f32_ubyte1_e32 v37, v37
	v_pk_fma_f32 v[20:21], v[40:41], v[88:89], v[20:21]
	v_lshlrev_b32_e32 v94, 16, v47
	v_and_b32_e32 v95, s101, v47
	v_fma_f32 v47, -v46, v46, 1.0
	v_mul_f32_e32 v37, v25, v37
	v_cvt_pk_bf16_f32 v42, v20, v21
	v_cvt_f32_f16_e32 v20, v33
	v_cvt_f32_f16_sdwa v21, v33 dst_sel:DWORD dst_unused:UNUSED_PAD src0_sel:WORD_1
	v_max_f32_e32 v47, 0, v47
	v_mul_f32_e32 v37, s100, v37
	v_sqrt_f32_e32 v96, v47
	v_exp_f32_e32 v47, v37
	v_pk_mul_f32 v[14:15], v[54:55], v[14:15]
	v_cvt_f32_ubyte1_e32 v39, v34
	v_pk_fma_f32 v[14:15], v[90:91], v[20:21], v[14:15]
	s_waitcnt lgkmcnt(0)
	v_cvt_f32_f16_e32 v20, v104
	v_cvt_f32_f16_sdwa v21, v104 dst_sel:DWORD dst_unused:UNUSED_PAD src0_sel:WORD_1
	v_fma_f32 v37, -v47, v47, 1.0
	v_max_f32_e32 v37, 0, v37
	v_cvt_f32_ubyte0_e32 v38, v34
	v_sqrt_f32_e32 v97, v37
	v_cvt_f32_ubyte1_e32 v37, v36
	v_cvt_f32_ubyte0_e32 v36, v36
	v_pk_mul_f32 v[38:39], v[38:39], s[52:53] op_sel_hi:[1,0]
	v_pk_add_f32 v[20:21], v[14:15], v[20:21]
	v_pk_mul_f32 v[36:37], v[36:37], s[52:53] op_sel_hi:[1,0]
	v_cvt_f32_ubyte1_e32 v41, v35
	v_cvt_f32_ubyte0_e32 v40, v35
	v_pk_mul_f32 v[20:21], v[38:39], v[20:21]
	v_pk_mul_f32 v[34:35], v[40:41], s[52:53] op_sel_hi:[1,0]
	v_pk_fma_f32 v[20:21], v[36:37], v[92:93], v[20:21]
	v_pk_mul_f32 v[14:15], v[46:47], v[14:15]
	v_pk_fma_f32 v[20:21], v[34:35], v[94:95], v[20:21]
	v_lshlrev_b32_e32 v34, 16, v29
	v_cvt_pk_bf16_f32 v38, v20, v21
	v_cvt_f32_f16_e32 v20, v27
	v_cvt_f32_f16_sdwa v21, v27 dst_sel:DWORD dst_unused:UNUSED_PAD src0_sel:WORD_1
	ds_read_b32 v27, v100
	v_and_b32_e32 v35, s101, v29
	v_cvt_f32_ubyte1_e32 v37, v31
	v_pk_fma_f32 v[14:15], v[96:97], v[20:21], v[14:15]
	v_lshlrev_b32_e32 v20, 16, v28
	v_and_b32_e32 v21, s101, v28
	s_waitcnt lgkmcnt(0)
	v_cvt_f32_f16_e32 v28, v27
	v_cvt_f32_f16_sdwa v29, v27 dst_sel:DWORD dst_unused:UNUSED_PAD src0_sel:WORD_1
	v_cvt_f32_ubyte0_e32 v36, v31
	v_cvt_f32_ubyte1_e32 v33, v32
	v_cvt_f32_ubyte0_e32 v32, v32
	v_pk_add_f32 v[28:29], v[14:15], v[28:29]
	v_pk_mul_f32 v[36:37], v[36:37], s[52:53] op_sel_hi:[1,0]
	v_pk_mul_f32 v[32:33], v[32:33], s[52:53] op_sel_hi:[1,0]
	v_pk_mul_f32 v[28:29], v[36:37], v[28:29]
	s_nop 0
	v_pk_fma_f32 v[20:21], v[32:33], v[20:21], v[28:29]
	v_cvt_f32_ubyte1_e32 v29, v30
	v_cvt_f32_ubyte0_e32 v28, v30
	v_pk_mul_f32 v[28:29], v[28:29], s[52:53] op_sel_hi:[1,0]
	s_nop 0
	v_pk_fma_f32 v[20:21], v[28:29], v[34:35], v[20:21]
	s_nop 0
	v_cvt_pk_bf16_f32 v27, v20, v21
	v_add_co_u32_e32 v20, vcc, s16, v16
	s_mov_b32 s16, 0x5a1d000
	s_nop 0
	v_addc_co_u32_e32 v21, vcc, 0, v17, vcc
	v_add_co_u32_e32 v28, vcc, s16, v16
	s_mov_b32 s16, 0x5a1e000
	s_nop 0
	v_addc_co_u32_e32 v29, vcc, 0, v17, vcc
	global_store_dword v[28:29], v27, off offset:-4096
	global_store_dword v[20:21], v38, off offset:2048
	global_store_dword v[28:29], v42, off
	global_store_dword v[28:29], v48, off offset:2048
	v_add_co_u32_e32 v20, vcc, s16, v16
	s_movk_i32 s16, 0xe000
	s_nop 0
	v_addc_co_u32_e32 v21, vcc, 0, v17, vcc
	v_add_co_u32_e32 v16, vcc, 0x5a1f000, v16
	s_mov_b32 s17, -1
	s_nop 0
	v_addc_co_u32_e32 v17, vcc, 0, v17, vcc
	v_lshl_add_u64 v[8:9], v[8:9], 0, s[16:17]
	global_store_dword v[20:21], v52, off
	global_store_dword v[20:21], v58, off offset:2048
	global_store_dword v[16:17], v19, off
	global_store_dword v[16:17], v18, off offset:2048
	s_cbranch_scc0 .LBB0_61
	s_add_i32 s8, s8, s3
	s_cmpk_gt_i32 s8, 0xff
	s_barrier
	s_cbranch_scc0 .LBB0_58

; __device__ __forceinline__ void phase4a(KP pp) {
;     ...
;     { const h16* LA = LAB + base; const h16* Bv = LAB + (size_t)CT * D + base;
;       float s0 = 0.f, s1 = 0.f, h0 = 0.f, h1 = 0.f;
; #pragma unroll 8
;       for (int t = 0; t < 64; ++t) { h16x2 la = *(const h16x2*)(LA + (size_t)t * D), b = *(const h16x2*)(Bv + (size_t)t * D);
;         float l0 = (float)la[0], l1 = (float)la[1];
;         h0 = __expf(l0) * h0 + (float)b[0]; h1 = __expf(l1) * h1 + (float)b[1]; s0 += l0; s1 += l1; }
;       *(float2*)(AGGA + (size_t)seg * D + c2) = float2{__expf(s0), __expf(s1)}; *(float2*)(AGGH + (size_t)seg * D + c2) = float2{h0, h1}; }
;     { const h16* LA = LAB + (size_t)2 * CT * D + base; const h16* Bv = LAB + (size_t)3 * CT * D + base;
.LBB0_92:
	s_mov_b32 s100, 0x3fb8aa3b
	s_mov_b32 s101, 0xffff0000
	v_lshl_add_u64 v[10:11], v[8:9], 0, s[16:17]
	v_add_co_u32_e32 v16, vcc, 0x9a00000, v10
	s_mov_b32 s18, 0x9a01000
	s_nop 0
	v_addc_co_u32_e32 v17, vcc, 0, v11, vcc
	global_load_dword v21, v[16:17], off
	v_add_co_u32_e32 v18, vcc, 0xba00000, v10
	s_add_u32 s16, s16, 0x4000
	s_nop 0
	v_addc_co_u32_e32 v19, vcc, 0, v11, vcc
	global_load_dword v25, v[18:19], off
	s_addc_u32 s17, s17, 0
	s_cmp_eq_u32 s16, 0x20000
	s_waitcnt vmcnt(1)
	v_cvt_f32_f16_e32 v20, v21
	v_cvt_f32_f16_sdwa v21, v21 dst_sel:DWORD dst_unused:UNUSED_PAD src0_sel:WORD_1
	v_mul_f32_e32 v22, s100, v20
	v_mul_f32_e32 v23, s100, v21
	v_pk_add_f32 v[14:15], v[14:15], v[20:21]
	global_load_dword v17, v[16:17], off offset:2048
	s_nop 0
	global_load_dword v21, v[18:19], off offset:2048
	v_exp_f32_e32 v22, v22
	v_exp_f32_e32 v23, v23
	s_waitcnt vmcnt(2)
	v_cvt_f32_f16_e32 v24, v25
	v_cvt_f32_f16_sdwa v25, v25 dst_sel:DWORD dst_unused:UNUSED_PAD src0_sel:WORD_1
	v_pk_fma_f32 v[12:13], v[12:13], v[22:23], v[24:25]
	s_waitcnt vmcnt(1)
	v_cvt_f32_f16_e32 v16, v17
	v_cvt_f32_f16_sdwa v17, v17 dst_sel:DWORD dst_unused:UNUSED_PAD src0_sel:WORD_1
	s_waitcnt vmcnt(0)
	v_cvt_f32_f16_e32 v20, v21
	v_cvt_f32_f16_sdwa v21, v21 dst_sel:DWORD dst_unused:UNUSED_PAD src0_sel:WORD_1
	v_mul_f32_e32 v18, s100, v16
	v_mul_f32_e32 v19, s100, v17
	v_exp_f32_e32 v18, v18
	v_exp_f32_e32 v19, v19
	v_pk_add_f32 v[14:15], v[14:15], v[16:17]
	v_add_co_u32_e32 v16, vcc, s18, v10
	s_mov_b32 s18, 0x9a02000
	s_nop 0
	v_addc_co_u32_e32 v17, vcc, 0, v11, vcc
	v_pk_fma_f32 v[12:13], v[12:13], v[18:19], v[20:21]
	v_add_co_u32_e32 v18, vcc, s18, v10
	s_mov_b32 s18, 0xba01000
	s_nop 0
	v_addc_co_u32_e32 v19, vcc, 0, v11, vcc
	global_load_dword v25, v[18:19], off offset:-4096
	v_add_co_u32_e32 v20, vcc, s18, v10
	s_mov_b32 s18, 0xba02000
	s_nop 0
	v_addc_co_u32_e32 v21, vcc, 0, v11, vcc
	v_add_co_u32_e32 v22, vcc, s18, v10
	s_mov_b32 s18, 0x9a03000
	s_nop 0
	v_addc_co_u32_e32 v23, vcc, 0, v11, vcc
	global_load_dword v29, v[22:23], off offset:-4096
	s_waitcnt vmcnt(1)
	v_cvt_f32_f16_e32 v24, v25
	v_cvt_f32_f16_sdwa v25, v25 dst_sel:DWORD dst_unused:UNUSED_PAD src0_sel:WORD_1
	v_mul_f32_e32 v26, s100, v24
	v_mul_f32_e32 v27, s100, v25
	v_pk_add_f32 v[14:15], v[14:15], v[24:25]
	global_load_dword v17, v[16:17], off offset:2048
	s_nop 0
	global_load_dword v25, v[20:21], off offset:2048
	v_exp_f32_e32 v26, v26
	v_exp_f32_e32 v27, v27
	s_waitcnt vmcnt(2)
	v_cvt_f32_f16_e32 v28, v29
	v_cvt_f32_f16_sdwa v29, v29 dst_sel:DWORD dst_unused:UNUSED_PAD src0_sel:WORD_1
	v_pk_fma_f32 v[12:13], v[12:13], v[26:27], v[28:29]
	s_waitcnt vmcnt(1)
	v_cvt_f32_f16_e32 v16, v17
	v_cvt_f32_f16_sdwa v17, v17 dst_sel:DWORD dst_unused:UNUSED_PAD src0_sel:WORD_1
	s_waitcnt vmcnt(0)
	v_cvt_f32_f16_e32 v24, v25
	v_cvt_f32_f16_sdwa v25, v25 dst_sel:DWORD dst_unused:UNUSED_PAD src0_sel:WORD_1
	v_mul_f32_e32 v20, s100, v16
	v_mul_f32_e32 v21, s100, v17
	v_exp_f32_e32 v20, v20
	v_exp_f32_e32 v21, v21
	v_pk_add_f32 v[14:15], v[14:15], v[16:17]
	v_pk_fma_f32 v[12:13], v[12:13], v[20:21], v[24:25]
	global_load_dword v17, v[18:19], off
	global_load_dword v25, v[22:23], off
	s_waitcnt vmcnt(1)
	v_cvt_f32_f16_e32 v16, v17
	v_cvt_f32_f16_sdwa v17, v17 dst_sel:DWORD dst_unused:UNUSED_PAD src0_sel:WORD_1
	s_waitcnt vmcnt(0)
	v_cvt_f32_f16_e32 v24, v25
	v_cvt_f32_f16_sdwa v25, v25 dst_sel:DWORD dst_unused:UNUSED_PAD src0_sel:WORD_1
	v_mul_f32_e32 v20, s100, v16
	v_mul_f32_e32 v21, s100, v17
	v_exp_f32_e32 v20, v20
	v_exp_f32_e32 v21, v21
	v_pk_add_f32 v[14:15], v[14:15], v[16:17]
	v_pk_fma_f32 v[12:13], v[12:13], v[20:21], v[24:25]
	global_load_dword v17, v[18:19], off offset:2048
	global_load_dword v21, v[22:23], off offset:2048
	s_waitcnt vmcnt(1)
	v_cvt_f32_f16_e32 v16, v17
	v_cvt_f32_f16_sdwa v17, v17 dst_sel:DWORD dst_unused:UNUSED_PAD src0_sel:WORD_1
	s_waitcnt vmcnt(0)
	v_cvt_f32_f16_e32 v20, v21
	v_cvt_f32_f16_sdwa v21, v21 dst_sel:DWORD dst_unused:UNUSED_PAD src0_sel:WORD_1
	v_mul_f32_e32 v18, s100, v16
	v_mul_f32_e32 v19, s100, v17
	v_exp_f32_e32 v18, v18
	v_exp_f32_e32 v19, v19
	v_pk_add_f32 v[14:15], v[14:15], v[16:17]
	v_add_co_u32_e32 v16, vcc, s18, v10
	v_pk_fma_f32 v[12:13], v[12:13], v[18:19], v[20:21]
	s_nop 0
	v_addc_co_u32_e32 v17, vcc, 0, v11, vcc
	global_load_dword v19, v[16:17], off
	s_mov_b32 s18, 0xba03000
	v_add_co_u32_e32 v10, vcc, s18, v10
	s_nop 1
	v_addc_co_u32_e32 v11, vcc, 0, v11, vcc
	global_load_dword v23, v[10:11], off
	s_waitcnt vmcnt(1)
	v_cvt_f32_f16_e32 v18, v19
	v_cvt_f32_f16_sdwa v19, v19 dst_sel:DWORD dst_unused:UNUSED_PAD src0_sel:WORD_1
	v_mul_f32_e32 v20, s100, v18
	v_mul_f32_e32 v21, s100, v19
	v_pk_add_f32 v[14:15], v[14:15], v[18:19]
	global_load_dword v16, v[16:17], off offset:2048
	s_nop 0
	global_load_dword v19, v[10:11], off offset:2048
	v_exp_f32_e32 v20, v20
	v_exp_f32_e32 v21, v21
	s_waitcnt vmcnt(2)
	v_cvt_f32_f16_e32 v22, v23
	v_cvt_f32_f16_sdwa v23, v23 dst_sel:DWORD dst_unused:UNUSED_PAD src0_sel:WORD_1
	v_pk_fma_f32 v[12:13], v[12:13], v[20:21], v[22:23]
	s_waitcnt vmcnt(1)
	v_cvt_f32_f16_e32 v10, v16
	v_cvt_f32_f16_sdwa v11, v16 dst_sel:DWORD dst_unused:UNUSED_PAD src0_sel:WORD_1
	s_waitcnt vmcnt(0)
	v_cvt_f32_f16_e32 v18, v19
	v_cvt_f32_f16_sdwa v19, v19 dst_sel:DWORD dst_unused:UNUSED_PAD src0_sel:WORD_1
	v_mul_f32_e32 v16, s100, v10
	v_mul_f32_e32 v17, s100, v11
	v_exp_f32_e32 v16, v16
	v_exp_f32_e32 v17, v17
	v_pk_add_f32 v[14:15], v[14:15], v[10:11]
	v_pk_fma_f32 v[12:13], v[12:13], v[16:17], v[18:19]
	s_cbranch_scc0 .LBB0_92
	v_mul_f32_e32 v8, s100, v14
	v_exp_f32_e32 v10, v8
	v_mul_f32_e32 v8, s100, v15
	v_exp_f32_e32 v11, v8
	v_lshl_add_u64 v[8:9], v[6:7], 0, s[8:9]
	s_lshl_b64 s[8:9], s[4:5], 12
	v_lshl_add_u64 v[14:15], v[2:3], 0, s[8:9]
	global_store_dwordx2 v[14:15], v[10:11], off
	v_lshl_add_u64 v[10:11], v[4:5], 0, s[8:9]
	global_store_dwordx2 v[10:11], v[12:13], off
	v_mov_b32_e32 v10, 0
	s_movk_i32 s5, 0xffc0
	v_mov_b32_e32 v11, v10
	v_mov_b32_e32 v12, v10
	v_mov_b32_e32 v13, v10
; __device__ __forceinline__ void phase4a(KP pp) {
;     ...
;     { const h16* LA = LAB + (size_t)2 * CT * D + base; const h16* Bv = LAB + (size_t)3 * CT * D + base;
;       float s0 = 0.f, s1 = 0.f, h0 = 0.f, h1 = 0.f;
; #pragma unroll 8
;       for (int t = 63; t >= 0; --t) { h16x2 la = *(const h16x2*)(LA + (size_t)t * D), b = *(const h16x2*)(Bv + (size_t)t * D);
;         float l0 = (float)la[0], l1 = (float)la[1];
;         h0 = __expf(l0) * h0 + (float)b[0]; h1 = __expf(l1) * h1 + (float)b[1]; s0 += l0; s1 += l1; }
;       *(float2*)(AGGA + (size_t)(256 + seg) * D + c2) = float2{__expf(s0), __expf(s1)}; *(float2*)(AGGH + (size_t)(256 + seg) * D + c2) = float2{h0, h1}; }
.LBB0_94:
	s_mov_b32 s100, 0x3fb8aa3b
	s_mov_b32 s101, 0xffff0000
	v_add_co_u32_e32 v14, vcc, 0x3000, v8
	s_mov_b32 s16, 0x2002000
	s_nop 0
	v_addc_co_u32_e32 v15, vcc, 0, v9, vcc
	global_load_dword v19, v[14:15], off offset:2048
	v_add_co_u32_e32 v16, vcc, 0x2003000, v8
	s_add_i32 s5, s5, 8
	s_nop 0
	v_addc_co_u32_e32 v17, vcc, 0, v9, vcc
	global_load_dword v23, v[16:17], off offset:2048
	s_cmp_eq_u32 s5, 0
	s_waitcnt vmcnt(1)
	v_cvt_f32_f16_e32 v18, v19
	v_cvt_f32_f16_sdwa v19, v19 dst_sel:DWORD dst_unused:UNUSED_PAD src0_sel:WORD_1
	v_mul_f32_e32 v20, s100, v18
	v_mul_f32_e32 v21, s100, v19
	v_pk_add_f32 v[12:13], v[12:13], v[18:19]
	global_load_dword v15, v[14:15], off
	s_nop 0
	global_load_dword v19, v[16:17], off
	v_exp_f32_e32 v20, v20
	v_exp_f32_e32 v21, v21
	s_waitcnt vmcnt(2)
	v_cvt_f32_f16_e32 v22, v23
	v_cvt_f32_f16_sdwa v23, v23 dst_sel:DWORD dst_unused:UNUSED_PAD src0_sel:WORD_1
	v_pk_fma_f32 v[10:11], v[10:11], v[20:21], v[22:23]
	s_waitcnt vmcnt(1)
	v_cvt_f32_f16_e32 v14, v15
	v_cvt_f32_f16_sdwa v15, v15 dst_sel:DWORD dst_unused:UNUSED_PAD src0_sel:WORD_1
	s_waitcnt vmcnt(0)
	v_cvt_f32_f16_e32 v18, v19
	v_cvt_f32_f16_sdwa v19, v19 dst_sel:DWORD dst_unused:UNUSED_PAD src0_sel:WORD_1
	v_mul_f32_e32 v16, s100, v14
	v_mul_f32_e32 v17, s100, v15
	v_exp_f32_e32 v16, v16
	v_exp_f32_e32 v17, v17
	v_pk_add_f32 v[12:13], v[12:13], v[14:15]
	v_add_co_u32_e32 v14, vcc, s99, v8
	v_pk_fma_f32 v[10:11], v[10:11], v[16:17], v[18:19]
	s_nop 0
	v_addc_co_u32_e32 v15, vcc, 0, v9, vcc
	global_load_dword v19, v[14:15], off offset:2048
	v_add_co_u32_e32 v16, vcc, s16, v8
	s_mov_b32 s16, 0x2001000
	s_nop 0
	v_addc_co_u32_e32 v17, vcc, 0, v9, vcc
	global_load_dword v23, v[16:17], off offset:2048
	s_waitcnt vmcnt(1)
	v_cvt_f32_f16_e32 v18, v19
	v_cvt_f32_f16_sdwa v19, v19 dst_sel:DWORD dst_unused:UNUSED_PAD src0_sel:WORD_1
	v_mul_f32_e32 v20, s100, v18
	v_mul_f32_e32 v21, s100, v19
	v_pk_add_f32 v[12:13], v[12:13], v[18:19]
	global_load_dword v15, v[14:15], off
	s_nop 0
	global_load_dword v19, v[16:17], off
	v_exp_f32_e32 v20, v20
	v_exp_f32_e32 v21, v21
	s_waitcnt vmcnt(2)
	v_cvt_f32_f16_e32 v22, v23
	v_cvt_f32_f16_sdwa v23, v23 dst_sel:DWORD dst_unused:UNUSED_PAD src0_sel:WORD_1
	v_pk_fma_f32 v[10:11], v[10:11], v[20:21], v[22:23]
	s_waitcnt vmcnt(1)
	v_cvt_f32_f16_e32 v14, v15
	v_cvt_f32_f16_sdwa v15, v15 dst_sel:DWORD dst_unused:UNUSED_PAD src0_sel:WORD_1
	s_waitcnt vmcnt(0)
	v_cvt_f32_f16_e32 v18, v19
	v_cvt_f32_f16_sdwa v19, v19 dst_sel:DWORD dst_unused:UNUSED_PAD src0_sel:WORD_1
	v_mul_f32_e32 v16, s100, v14
	v_mul_f32_e32 v17, s100, v15
	v_exp_f32_e32 v16, v16
	v_exp_f32_e32 v17, v17
	v_pk_add_f32 v[12:13], v[12:13], v[14:15]
	v_add_co_u32_e32 v14, vcc, s58, v8
	v_pk_fma_f32 v[10:11], v[10:11], v[16:17], v[18:19]
	s_nop 0
	v_addc_co_u32_e32 v15, vcc, 0, v9, vcc
	global_load_dword v19, v[14:15], off offset:2048
	v_add_co_u32_e32 v16, vcc, s16, v8
	s_brev_b32 s16, 64
	s_nop 0
	v_addc_co_u32_e32 v17, vcc, 0, v9, vcc
	global_load_dword v23, v[16:17], off offset:2048
	s_waitcnt vmcnt(1)
	v_cvt_f32_f16_e32 v18, v19
	v_cvt_f32_f16_sdwa v19, v19 dst_sel:DWORD dst_unused:UNUSED_PAD src0_sel:WORD_1
	v_mul_f32_e32 v20, s100, v18
	v_mul_f32_e32 v21, s100, v19
	v_pk_add_f32 v[12:13], v[12:13], v[18:19]
	global_load_dword v15, v[14:15], off
	s_nop 0
	global_load_dword v19, v[16:17], off
	v_exp_f32_e32 v20, v20
	v_exp_f32_e32 v21, v21
	s_waitcnt vmcnt(2)
	v_cvt_f32_f16_e32 v22, v23
	v_cvt_f32_f16_sdwa v23, v23 dst_sel:DWORD dst_unused:UNUSED_PAD src0_sel:WORD_1
	v_pk_fma_f32 v[10:11], v[10:11], v[20:21], v[22:23]
	s_waitcnt vmcnt(1)
	v_cvt_f32_f16_e32 v14, v15
	v_cvt_f32_f16_sdwa v15, v15 dst_sel:DWORD dst_unused:UNUSED_PAD src0_sel:WORD_1
	s_waitcnt vmcnt(0)
	v_cvt_f32_f16_e32 v18, v19
	v_cvt_f32_f16_sdwa v19, v19 dst_sel:DWORD dst_unused:UNUSED_PAD src0_sel:WORD_1
	v_mul_f32_e32 v16, s100, v14
	v_mul_f32_e32 v17, s100, v15
	v_exp_f32_e32 v16, v16
	v_exp_f32_e32 v17, v17
	v_pk_add_f32 v[12:13], v[12:13], v[14:15]
	v_add_co_u32_e32 v14, vcc, s16, v8
	v_pk_fma_f32 v[10:11], v[10:11], v[16:17], v[18:19]
	global_load_dword v16, v[8:9], off offset:2048
	v_addc_co_u32_e32 v15, vcc, 0, v9, vcc
	global_load_dword v21, v[14:15], off offset:2048
	s_waitcnt vmcnt(1)
	v_cvt_f32_f16_sdwa v17, v16 dst_sel:DWORD dst_unused:UNUSED_PAD src0_sel:WORD_1
	v_cvt_f32_f16_e32 v16, v16
	s_waitcnt vmcnt(0)
	v_cvt_f32_f16_e32 v20, v21
	v_mul_f32_e32 v19, s100, v17
	v_mul_f32_e32 v18, s100, v16
	v_exp_f32_e32 v18, v18
	v_exp_f32_e32 v19, v19
	v_cvt_f32_f16_sdwa v21, v21 dst_sel:DWORD dst_unused:UNUSED_PAD src0_sel:WORD_1
	v_pk_add_f32 v[12:13], v[12:13], v[16:17]
	v_pk_fma_f32 v[10:11], v[10:11], v[18:19], v[20:21]
	global_load_dword v16, v[8:9], off
	global_load_dword v19, v[14:15], off
	v_lshl_add_u64 v[8:9], v[8:9], 0, s[46:47]
	s_waitcnt vmcnt(1)
	v_cvt_f32_f16_sdwa v15, v16 dst_sel:DWORD dst_unused:UNUSED_PAD src0_sel:WORD_1
	v_cvt_f32_f16_e32 v14, v16
	s_waitcnt vmcnt(0)
	v_cvt_f32_f16_e32 v18, v19
	v_cvt_f32_f16_sdwa v19, v19 dst_sel:DWORD dst_unused:UNUSED_PAD src0_sel:WORD_1
	v_mul_f32_e32 v17, s100, v15
	v_mul_f32_e32 v16, s100, v14
	v_exp_f32_e32 v16, v16
	v_exp_f32_e32 v17, v17
	v_pk_add_f32 v[12:13], v[12:13], v[14:15]
	v_pk_fma_f32 v[10:11], v[10:11], v[16:17], v[18:19]
	s_cbranch_scc0 .LBB0_94
	v_mul_f32_e32 v8, s100, v12
	v_mul_f32_e32 v9, s100, v13
	v_exp_f32_e32 v8, v8
	v_exp_f32_e32 v9, v9
	s_add_u32 s8, s8, 0x100000
	s_addc_u32 s9, s9, 0
	v_lshl_add_u64 v[12:13], v[2:3], 0, s[8:9]
	s_add_i32 s4, s4, s3
	global_store_dwordx2 v[12:13], v[8:9], off
	v_lshl_add_u64 v[8:9], v[4:5], 0, s[8:9]
	s_cmpk_gt_i32 s4, 0xff
	global_store_dwordx2 v[8:9], v[10:11], off
	s_cbranch_scc0 .LBB0_91

; __device__ __forceinline__ unsigned pk2(float lo, float hi) { f32x2 v = {lo, hi}; return __builtin_bit_cast(unsigned, __builtin_convertvector(v, hwbf16x2)); }
; __device__ __forceinline__ void phase2(KP pp, int l, int c) {
;     ...
;       for (int tt = 0; tt < 8; ++tt) {
;         const int tl = tg * 8 + tt;
;         float y[8];
; #pragma unroll
;         for (int e = 0; e < 8; ++e) y[e] = bb[e];
; #pragma unroll
;         for (int k = 0; k < 4; ++k) {
;           uint4 q = *(const uint4*)(lbase + (tl + 8 + k - 2) * RS);
;           y[0] += bflo(q.x) * w[k][0]; y[1] += bfhi(q.x) * w[k][1]; y[2] += bflo(q.y) * w[k][2]; y[3] += bfhi(q.y) * w[k][3];
;           y[4] += bflo(q.z) * w[k][4]; y[5] += bfhi(q.z) * w[k][5]; y[6] += bflo(q.w) * w[k][6]; y[7] += bfhi(q.w) * w[k][7];
;         }
;         uint4 oc; oc.x = pk2(y[0], y[1]); oc.y = pk2(y[2], y[3]); oc.z = pk2(y[4], y[5]); oc.w = pk2(y[6], y[7]);
;         st16_wt(XC, (unsigned)((t0 + tl) * D + c0) * 2u, oc.x, oc.y, oc.z, oc.w);
;       }
.LBB0_146:
	s_mov_b32 s100, 0x3fb8aa3b
	s_mov_b32 s101, 0xffff0000
	v_add_u32_e32 v142, s4, v105
	ds_read_b128 v[78:81], v142
	ds_read_b128 v[120:123], v142 offset:1056
	s_mov_b32 s18, s10
	s_mov_b32 s19, s11
	s_addk_i32 s4, 0x420
	s_waitcnt lgkmcnt(1)
	v_lshlrev_b32_e32 v128, 16, v80
	v_and_b32_e32 v129, s101, v80
	v_lshlrev_b32_e32 v130, 16, v81
	v_and_b32_e32 v131, s101, v81
	ds_read_b128 v[80:83], v142 offset:528
	v_lshlrev_b32_e32 v124, 16, v78
	v_and_b32_e32 v125, s101, v78
	v_lshlrev_b32_e32 v126, 16, v79
	v_and_b32_e32 v127, s101, v79
	s_waitcnt lgkmcnt(0)
	v_lshlrev_b32_e32 v88, 16, v80
	v_and_b32_e32 v89, s101, v80
	v_lshlrev_b32_e32 v84, 16, v81
	v_and_b32_e32 v85, s101, v81
	v_lshlrev_b32_e32 v80, 16, v82
	v_and_b32_e32 v81, s101, v82
	v_lshlrev_b32_e32 v78, 16, v83
	v_and_b32_e32 v79, s101, v83
	v_lshlrev_b32_e32 v132, 16, v120
	v_and_b32_e32 v133, s101, v120
	v_lshlrev_b32_e32 v90, 16, v121
	v_and_b32_e32 v91, s101, v121
	v_lshlrev_b32_e32 v86, 16, v122
	v_and_b32_e32 v87, s101, v122
	v_lshlrev_b32_e32 v82, 16, v123
	v_and_b32_e32 v83, s101, v123
	ds_read_b128 v[120:123], v142 offset:1584
	v_pk_fma_f32 v[124:125], v[40:41], v[124:125], v[72:73]
	s_cmpk_lg_i32 s4, 0x1ce0
	v_pk_fma_f32 v[124:125], v[48:49], v[88:89], v[124:125]
	v_pk_fma_f32 v[88:89], v[40:41], v[88:89], v[72:73]
	s_waitcnt lgkmcnt(0)
	v_lshlrev_b32_e32 v134, 16, v120
	v_and_b32_e32 v135, s101, v120
	v_lshlrev_b32_e32 v136, 16, v121
	v_and_b32_e32 v137, s101, v121
	v_pk_fma_f32 v[120:121], v[42:43], v[126:127], v[74:75]
	v_lshlrev_b32_e32 v138, 16, v122
	v_pk_fma_f32 v[120:121], v[50:51], v[84:85], v[120:121]
	v_and_b32_e32 v139, s101, v122
	v_pk_fma_f32 v[120:121], v[54:55], v[90:91], v[120:121]
	v_pk_fma_f32 v[124:125], v[52:53], v[132:133], v[124:125]
	v_pk_fma_f32 v[126:127], v[58:59], v[136:137], v[120:121]
	v_pk_fma_f32 v[120:121], v[36:37], v[128:129], v[68:69]
	v_lshlrev_b32_e32 v140, 16, v123
	v_pk_fma_f32 v[120:121], v[44:45], v[80:81], v[120:121]
	v_and_b32_e32 v141, s101, v123
	v_pk_fma_f32 v[120:121], v[60:61], v[86:87], v[120:121]
	v_pk_fma_f32 v[124:125], v[56:57], v[134:135], v[124:125]
	v_pk_fma_f32 v[128:129], v[64:65], v[138:139], v[120:121]
	v_pk_fma_f32 v[120:121], v[38:39], v[130:131], v[70:71]
	v_cvt_pk_bf16_f32 v122, v128, v129
	v_pk_fma_f32 v[120:121], v[46:47], v[78:79], v[120:121]
	v_pk_fma_f32 v[84:85], v[42:43], v[84:85], v[74:75]
	v_pk_fma_f32 v[120:121], v[62:63], v[82:83], v[120:121]
	v_pk_fma_f32 v[80:81], v[36:37], v[80:81], v[68:69]
	v_pk_fma_f32 v[130:131], v[66:67], v[140:141], v[120:121]
	v_cvt_pk_bf16_f32 v120, v124, v125
	v_cvt_pk_bf16_f32 v121, v126, v127
	v_cvt_pk_bf16_f32 v123, v130, v131
	v_add_u32_e32 v124, 0xfffff800, v119
	buffer_store_dwordx4 v[120:123], v124, s[16:19], 0 offen sc1
	ds_read_b128 v[120:123], v142 offset:2112
	v_pk_fma_f32 v[78:79], v[38:39], v[78:79], v[70:71]
	v_pk_fma_f32 v[88:89], v[48:49], v[132:133], v[88:89]
	v_pk_fma_f32 v[84:85], v[50:51], v[90:91], v[84:85]
	v_pk_fma_f32 v[80:81], v[44:45], v[86:87], v[80:81]
	v_pk_fma_f32 v[78:79], v[46:47], v[82:83], v[78:79]
	s_waitcnt lgkmcnt(0)
	v_lshlrev_b32_e32 v124, 16, v120
	v_and_b32_e32 v125, s101, v120
	v_pk_fma_f32 v[88:89], v[52:53], v[134:135], v[88:89]
	v_lshlrev_b32_e32 v120, 16, v121
	v_and_b32_e32 v121, s101, v121
	v_pk_fma_f32 v[84:85], v[54:55], v[136:137], v[84:85]
	v_lshlrev_b32_e32 v90, 16, v122
	v_and_b32_e32 v91, s101, v122
	v_pk_fma_f32 v[80:81], v[60:61], v[138:139], v[80:81]
	v_lshlrev_b32_e32 v86, 16, v123
	v_and_b32_e32 v87, s101, v123
	v_pk_fma_f32 v[78:79], v[62:63], v[140:141], v[78:79]
	v_pk_fma_f32 v[88:89], v[56:57], v[124:125], v[88:89]
	v_pk_fma_f32 v[84:85], v[58:59], v[120:121], v[84:85]
	v_pk_fma_f32 v[80:81], v[64:65], v[90:91], v[80:81]
	v_pk_fma_f32 v[82:83], v[66:67], v[86:87], v[78:79]
	v_cvt_pk_bf16_f32 v78, v88, v89
	v_cvt_pk_bf16_f32 v79, v84, v85
	v_cvt_pk_bf16_f32 v80, v80, v81
	v_cvt_pk_bf16_f32 v81, v82, v83
	buffer_store_dwordx4 v[78:81], v119, s[16:19], 0 offen sc1
	v_add_u32_e32 v119, 0x1000, v119
	s_cbranch_scc1 .LBB0_146
	s_mov_b64 s[4:5], 0

; __device__ __forceinline__ unsigned pk2(float lo, float hi) { f32x2 v = {lo, hi}; return __builtin_bit_cast(unsigned, __builtin_convertvector(v, hwbf16x2)); }
; __device__ __forceinline__ void phase2(KP pp, int l, int c) {
;     ...
;       for (int tt = 0; tt < 8; ++tt) {
;         const int tl = tl0 + tt, pos = pos0 + tl;
;         if (tt > 0) {
;           uint4 ue = *(const uint4*)(lbase + (tl + 8 + h - 1) * RS), ul = *(const uint4*)(lbase + (tl + 8 - h - 1) * RS);
;           s[0] += bflo(ue.x) - bflo(ul.x); s[1] += bfhi(ue.x) - bfhi(ul.x); s[2] += bflo(ue.y) - bflo(ul.y); s[3] += bfhi(ue.y) - bfhi(ul.y);
;           s[4] += bflo(ue.z) - bflo(ul.z); s[5] += bfhi(ue.z) - bfhi(ul.z); s[6] += bflo(ue.w) - bflo(ul.w); s[7] += bfhi(ue.w) - bfhi(ul.w);
;         }
;         const int lo = max(pos - h, 0), hi = min(pos + h, S);
;         const float inv = 1.f / (float)(hi - lo);
;         uint4 u = *(const uint4*)(lbase + (tl + 8) * RS);
;         uint4 o;
;         o.x = pk2(s[0] * inv - bflo(u.x), s[1] * inv - bfhi(u.x)); o.y = pk2(s[2] * inv - bflo(u.y), s[3] * inv - bfhi(u.y));
;         o.z = pk2(s[4] * inv - bflo(u.z), s[5] * inv - bfhi(u.z)); o.w = pk2(s[6] * inv - bflo(u.w), s[7] * inv - bfhi(u.w));
;         st16_wt(POOLED, (unsigned)((t0 + tl) * D + colbase + cc * 8) * 2u, o.x, o.y, o.z, o.w);
.LBB0_152:
	s_mov_b32 s100, 0x3fb8aa3b
	s_mov_b32 s101, 0xffff0000
	v_add_u32_e32 v64, s4, v47
	v_add_u32_e32 v65, s4, v46
	v_max_i32_e32 v52, 0, v64
	v_min_i32_e32 v53, s38, v65
	v_sub_u32_e32 v52, v53, v52
	v_cvt_f32_i32_e32 v52, v52
	v_add_u32_e32 v66, v50, v100
	v_add_u32_e32 v67, v100, v45
	s_add_i32 s4, s4, 2
	v_div_scale_f32 v53, s[18:19], v52, v52, 1.0
	v_rcp_f32_e32 v54, v53
	v_add_u32_e32 v48, 0x420, v48
	v_add_u32_e32 v49, 0x420, v49
	v_add_u32_e32 v50, 0x420, v50
	v_fma_f32 v55, -v53, v54, 1.0
	v_fmac_f32_e32 v54, v55, v54
	v_div_scale_f32 v55, vcc, 1.0, v52, 1.0
	v_mul_f32_e32 v56, v55, v54
	v_fma_f32 v57, -v53, v56, v55
	v_fmac_f32_e32 v56, v57, v54
	v_fma_f32 v53, -v53, v56, v55
	v_div_fmas_f32 v53, v53, v54, v56
	v_div_fixup_f32 v56, v53, v52, 1.0
	ds_read_b128 v[52:55], v66
	v_pk_mul_f32 v[60:61], v[56:57], v[42:43] op_sel_hi:[0,1]
	s_cmp_eq_u32 s4, 8
	s_waitcnt lgkmcnt(0)
	v_lshlrev_b32_e32 v58, 16, v52
	v_and_b32_e32 v59, s101, v52
	v_pk_add_f32 v[58:59], v[60:61], v[58:59] op_sel:[1,0] op_sel_hi:[0,1] neg_lo:[0,1] neg_hi:[0,1]
	v_cvt_pk_bf16_f32 v52, v58, v59
	v_lshlrev_b32_e32 v58, 16, v53
	v_and_b32_e32 v59, s101, v53
	v_pk_mul_f32 v[60:61], v[56:57], v[40:41] op_sel_hi:[0,1]
	v_pk_add_f32 v[58:59], v[60:61], v[58:59] op_sel:[1,0] op_sel_hi:[0,1] neg_lo:[0,1] neg_hi:[0,1]
	v_cvt_pk_bf16_f32 v53, v58, v59
	v_lshlrev_b32_e32 v58, 16, v54
	v_and_b32_e32 v59, s101, v54
	v_pk_mul_f32 v[60:61], v[56:57], v[38:39] op_sel_hi:[0,1]
	v_pk_add_f32 v[58:59], v[60:61], v[58:59] op_sel:[1,0] op_sel_hi:[0,1] neg_lo:[0,1] neg_hi:[0,1]
	v_cvt_pk_bf16_f32 v54, v58, v59
	v_lshlrev_b32_e32 v58, 16, v55
	v_and_b32_e32 v59, s101, v55
	v_pk_mul_f32 v[56:57], v[56:57], v[36:37] op_sel_hi:[0,1]
	v_pk_add_f32 v[56:57], v[56:57], v[58:59] op_sel:[1,0] op_sel_hi:[0,1] neg_lo:[0,1] neg_hi:[0,1]
	v_cvt_pk_bf16_f32 v55, v56, v57
	buffer_store_dwordx4 v[52:55], v67, s[8:11], 0 offen sc1
	ds_read_b128 v[52:55], v44 offset:528
	ds_read_b128 v[56:59], v51 offset:528
	v_add_u32_e32 v44, 1, v64
	v_add_u32_e32 v51, 1, v65
	v_max_i32_e32 v44, 0, v44
	s_waitcnt lgkmcnt(1)
	v_lshlrev_b32_e32 v61, 16, v52
	s_waitcnt lgkmcnt(0)
	v_lshlrev_b32_e32 v63, 16, v56
	v_and_b32_e32 v60, s101, v52
	v_and_b32_e32 v62, s101, v56
	v_pk_add_f32 v[60:61], v[60:61], v[62:63] neg_lo:[0,1] neg_hi:[0,1]
	v_min_i32_e32 v51, s38, v51
	v_pk_add_f32 v[42:43], v[42:43], v[60:61]
	v_lshlrev_b32_e32 v61, 16, v53
	v_lshlrev_b32_e32 v63, 16, v57
	v_and_b32_e32 v60, s101, v53
	v_and_b32_e32 v62, s101, v57
	v_sub_u32_e32 v44, v51, v44
	v_pk_add_f32 v[52:53], v[60:61], v[62:63] neg_lo:[0,1] neg_hi:[0,1]
	v_cvt_f32_i32_e32 v44, v44
	v_pk_add_f32 v[40:41], v[40:41], v[52:53]
	v_lshlrev_b32_e32 v53, 16, v54
	v_lshlrev_b32_e32 v57, 16, v58
	v_and_b32_e32 v52, s101, v54
	v_and_b32_e32 v56, s101, v58
	v_pk_add_f32 v[52:53], v[52:53], v[56:57] neg_lo:[0,1] neg_hi:[0,1]
	v_lshlrev_b32_e32 v57, 16, v59
	v_pk_add_f32 v[38:39], v[38:39], v[52:53]
	v_lshlrev_b32_e32 v53, 16, v55
	v_and_b32_e32 v52, s101, v55
	v_and_b32_e32 v56, s101, v59
	v_pk_add_f32 v[52:53], v[52:53], v[56:57] neg_lo:[0,1] neg_hi:[0,1]
	v_div_scale_f32 v51, s[18:19], v44, v44, 1.0
	v_pk_add_f32 v[36:37], v[36:37], v[52:53]
	v_rcp_f32_e32 v52, v51
	s_nop 0
	v_fma_f32 v53, -v51, v52, 1.0
	v_fmac_f32_e32 v52, v53, v52
	v_div_scale_f32 v53, vcc, 1.0, v44, 1.0
	v_mul_f32_e32 v54, v53, v52
	v_fma_f32 v55, -v51, v54, v53
	v_fmac_f32_e32 v54, v55, v52
	v_fma_f32 v51, -v51, v54, v53
	v_div_fmas_f32 v51, v51, v52, v54
	ds_read_b128 v[52:55], v66 offset:528
	v_div_fixup_f32 v44, v51, v44, 1.0
	v_pk_mul_f32 v[58:59], v[44:45], v[42:43] op_sel_hi:[0,1]
	s_waitcnt lgkmcnt(0)
	v_lshlrev_b32_e32 v56, 16, v52
	v_and_b32_e32 v57, s101, v52
	v_pk_add_f32 v[56:57], v[58:59], v[56:57] op_sel:[1,0] op_sel_hi:[0,1] neg_lo:[0,1] neg_hi:[0,1]
	v_cvt_pk_bf16_f32 v52, v56, v57
	v_lshlrev_b32_e32 v56, 16, v53
	v_and_b32_e32 v57, s101, v53
	v_pk_mul_f32 v[58:59], v[44:45], v[40:41] op_sel_hi:[0,1]
	v_pk_add_f32 v[56:57], v[58:59], v[56:57] op_sel:[1,0] op_sel_hi:[0,1] neg_lo:[0,1] neg_hi:[0,1]
	v_cvt_pk_bf16_f32 v53, v56, v57
	v_lshlrev_b32_e32 v56, 16, v54
	v_and_b32_e32 v57, s101, v54
	v_pk_mul_f32 v[58:59], v[44:45], v[38:39] op_sel_hi:[0,1]
	v_pk_add_f32 v[56:57], v[58:59], v[56:57] op_sel:[1,0] op_sel_hi:[0,1] neg_lo:[0,1] neg_hi:[0,1]
	v_cvt_pk_bf16_f32 v54, v56, v57
	v_lshlrev_b32_e32 v56, 16, v55
	v_and_b32_e32 v57, s101, v55
	v_pk_mul_f32 v[58:59], v[44:45], v[36:37] op_sel_hi:[0,1]
	v_pk_add_f32 v[56:57], v[58:59], v[56:57] op_sel:[1,0] op_sel_hi:[0,1] neg_lo:[0,1] neg_hi:[0,1]
	v_cvt_pk_bf16_f32 v55, v56, v57
	v_add_u32_e32 v45, 0x1000, v45
	buffer_store_dwordx4 v[52:55], v67, s[8:11], 0 offen offset:2048 sc1
	s_cbranch_scc1 .LBB0_123
